# BK=64 double-buffered K loop (128B-line LDS-DMA) for fc1 and input projection; LDS 80KB; norm steps batched loads
# speedup vs baseline: 1.1616x; 1.0742x over previous
_Z9trunk_fwd6Params:
	s_load_dword s5, s[0:1], 0x110
	v_writelane_b32 v249, s2, 0
	v_writelane_b32 v249, s0, 1
	s_load_dwordx2 s[18:19], s[0:1], 0x100
	s_mov_b32 s4, 0
	s_waitcnt lgkmcnt(0)
	s_cmp_eq_u32 s5, 0
	v_writelane_b32 v249, s1, 2
	s_cbranch_scc1 .LBB0_7
	v_and_b32_e32 v1, 0x3ff, v0
	v_cmp_eq_u32_e32 vcc, 0, v1
	s_and_saveexec_b64 s[0:1], vcc
	s_cbranch_execz .LBB0_3
	s_mov_b64 s[2:3], src_shared_base
	v_mov_b32_e32 v2, 0x12010
	v_mov_b32_e32 v3, s3
	v_mov_b32_e32 v1, 0
	v_writelane_b32 v247, s4, 57
	v_mov_b32_e32 v2, 0x12014
	v_writelane_b32 v247, s4, 58

.LBB0_23:
	v_lshl_add_u32 v44, v141, 1, s15
	ds_read_b128 v[134:137], v44 offset:12288
	v_lshl_add_u32 v123, v140, 1, s15
	ds_read_b128 v[174:177], v44 offset:13312
	ds_read_b128 v[32:35], v123
	ds_read_b128 v[36:39], v123 offset:1024
	s_add_i32 s0, s11, 1
	s_cmp_lg_u32 s11, 2
	s_cselect_b32 s22, s0, 0
	s_mul_i32 s0, s22, 0x2800
	s_addk_i32 s0, 0xd800
	s_cmp_lg_u32 s22, 0
	s_waitcnt lgkmcnt(0)
	v_mfma_f32_16x16x32_bf16 v[40:43], v[134:137], v[32:35], v[96:99]
	ds_read_b128 v[178:181], v44 offset:15360
	s_cselect_b32 s0, s0, 0x5000
	v_mov_b32_e32 v125, v153
	ds_read_b128 v[96:99], v44 offset:14336
	ds_read_b128 v[44:47], v123 offset:2048
	ds_read_b128 v[212:215], v123 offset:3072
	v_mfma_f32_16x16x32_bf16 v[108:111], v[174:177], v[32:35], v[108:111]
	ds_read_b128 v[216:219], v123 offset:4096
	ds_read_b128 v[220:223], v123 offset:5120
	s_waitcnt lgkmcnt(0)
	s_barrier
	v_mfma_f32_16x16x32_bf16 v[104:107], v[96:99], v[32:35], v[104:107]
	v_mov_b32_e32 v123, v153
	v_mov_b32_e32 v127, v153
	v_mfma_f32_16x16x32_bf16 v[100:103], v[178:181], v[32:35], v[100:103]
	v_lshl_add_u32 v32, s0, 1, v146
	v_add_u32_e32 v33, v32, v147
	v_max_f32_e32 v34, v42, v42
	v_mfma_f32_16x16x32_bf16 v[234:237], v[178:181], v[36:39], v[80:83]
	v_max_f32_e32 v35, v43, v43
	v_max_f32_e32 v34, 0, v34
	v_max_f32_e32 v35, 0, v35
	v_add_u32_e32 v80, v33, v148
	v_mfma_f32_16x16x32_bf16 v[238:241], v[134:137], v[44:47], v[76:79]
	v_mul_f32_e64 v34, v34, v34
	v_mul_f32_e64 v35, v35, v35
	v_add_u32_e32 v82, s10, v139
	v_ashrrev_i32_e32 v83, 31, v82
	v_add_u32_e32 v78, v33, v149
	v_add_u32_e32 v77, v33, v150
	v_add_u32_e32 v76, v33, v151
	v_add3_u32 v79, v32, v169, v155
	v_max_f32_e32 v32, v40, v40
	v_max_f32_e32 v33, v41, v41
	v_max_f32_e32 v32, 0, v32
	v_max_f32_e32 v33, 0, v33
	v_pk_mul_f32 v[32:33], v[32:33], v[32:33]
	v_mfma_f32_16x16x32_bf16 v[72:75], v[174:177], v[44:47], v[72:75]
	v_cvt_pk_bf16_f32 v32, v32, v33
	v_cvt_pk_bf16_f32 v33, v34, v35
	v_readlane_b32 s0, v249, 10
	v_mfma_f32_16x16x32_bf16 v[52:55], v[96:99], v[44:47], v[52:55]
	v_readlane_b32 s1, v249, 11
	v_mov_b32_e32 v129, v153
	v_mov_b32_e32 v131, v153
	v_mfma_f32_16x16x32_bf16 v[48:51], v[178:181], v[44:47], v[48:51]
	v_mov_b32_e32 v133, v153
	s_nop 2
	v_max_f32_e32 v52, v52, v52
	v_max_f32_e32 v53, v53, v53
	v_mfma_f32_16x16x32_bf16 v[44:47], v[134:137], v[212:215], v[68:71]
	v_max_f32_e32 v54, v54, v54
	v_max_f32_e32 v55, v55, v55
	v_max_f32_e32 v48, v48, v48
	v_lshl_add_u32 v68, v142, 1, v79
	ds_write_b64 v68, v[32:33]
	v_max_f32_e32 v32, v108, v108
	v_mfma_f32_16x16x32_bf16 v[92:95], v[134:137], v[36:39], v[92:95]
	v_lshl_add_u32 v69, v143, 1, v79
	v_lshl_add_u32 v70, v144, 1, v79
	v_lshl_add_u32 v71, v145, 1, v79
	v_mfma_f32_16x16x32_bf16 v[88:91], v[174:177], v[36:39], v[88:91]
	v_max_f32_e32 v49, v49, v49
	v_max_f32_e32 v50, v50, v50
	v_max_f32_e32 v51, v51, v51
	v_mfma_f32_16x16x32_bf16 v[84:87], v[96:99], v[36:39], v[84:87]
	v_max_f32_e32 v52, 0, v52
	v_max_f32_e32 v53, 0, v53
	v_max_f32_e32 v54, 0, v54
	v_mfma_f32_16x16x32_bf16 v[36:39], v[96:99], v[212:215], v[60:63]
	v_max_f32_e32 v55, 0, v55
	v_max_f32_e32 v48, 0, v48
	v_max_f32_e32 v49, 0, v49
	v_max_f32_e32 v60, 0, v32
	v_max_f32_e32 v61, v109, v109
	v_mfma_f32_16x16x32_bf16 v[32:35], v[178:181], v[212:215], v[56:59]
	v_max_f32_e32 v61, 0, v61
	s_nop 0
	v_max_f32_e32 v36, v36, v36
	v_max_f32_e32 v37, v37, v37
	v_max_f32_e32 v56, v110, v110
	v_max_f32_e32 v57, v111, v111
	v_max_f32_e32 v56, 0, v56
	v_max_f32_e32 v57, 0, v57
	v_pk_mul_f32 v[58:59], v[60:61], v[60:61]
	v_pk_mul_f32 v[56:57], v[56:57], v[56:57]
	v_cvt_pk_bf16_f32 v58, v58, v59
	v_cvt_pk_bf16_f32 v59, v56, v57
	ds_write_b64 v69, v[58:59]
	v_max_f32_e32 v56, v104, v104
	v_max_f32_e32 v57, v105, v105
	v_max_f32_e32 v58, v106, v106
	v_max_f32_e32 v59, v107, v107
	v_max_f32_e32 v56, 0, v56
	v_max_f32_e32 v57, 0, v57
	v_max_f32_e32 v58, 0, v58
	v_max_f32_e32 v59, 0, v59
	v_pk_mul_f32 v[56:57], v[56:57], v[56:57]
	v_pk_mul_f32 v[58:59], v[58:59], v[58:59]
	v_cvt_pk_bf16_f32 v56, v56, v57
	v_cvt_pk_bf16_f32 v57, v58, v59
	ds_write_b64 v70, v[56:57]
	v_max_f32_e32 v56, v100, v100
	v_max_f32_e32 v57, v101, v101
	v_max_f32_e32 v58, v102, v102
	v_max_f32_e32 v59, v103, v103
	v_max_f32_e32 v56, 0, v56
	v_max_f32_e32 v57, 0, v57
	v_max_f32_e32 v58, 0, v58
	v_max_f32_e32 v59, 0, v59
	v_pk_mul_f32 v[56:57], v[56:57], v[56:57]
	v_pk_mul_f32 v[58:59], v[58:59], v[58:59]
	v_cvt_pk_bf16_f32 v56, v56, v57
	v_cvt_pk_bf16_f32 v57, v58, v59
	ds_write_b64 v71, v[56:57]
	v_max_f32_e32 v56, v92, v92
	v_max_f32_e32 v57, v93, v93
	v_max_f32_e32 v58, v94, v94
	v_max_f32_e32 v59, v95, v95
	v_max_f32_e32 v56, 0, v56
	v_max_f32_e32 v57, 0, v57
	v_max_f32_e32 v58, 0, v58
	v_max_f32_e32 v59, 0, v59
	v_pk_mul_f32 v[56:57], v[56:57], v[56:57]
	v_pk_mul_f32 v[58:59], v[58:59], v[58:59]
	v_cvt_pk_bf16_f32 v56, v56, v57
	v_cvt_pk_bf16_f32 v57, v58, v59
	ds_write_b64 v68, v[56:57] offset:2048
	v_max_f32_e32 v56, v88, v88
	v_max_f32_e32 v57, v89, v89
	v_max_f32_e32 v58, v90, v90
	v_max_f32_e32 v59, v91, v91
	v_max_f32_e32 v56, 0, v56
	v_max_f32_e32 v57, 0, v57
	v_max_f32_e32 v58, 0, v58
	v_max_f32_e32 v59, 0, v59
	v_pk_mul_f32 v[56:57], v[56:57], v[56:57]
	v_pk_mul_f32 v[58:59], v[58:59], v[58:59]
	v_cvt_pk_bf16_f32 v56, v56, v57
	v_cvt_pk_bf16_f32 v57, v58, v59
	ds_write_b64 v69, v[56:57] offset:2048
	v_max_f32_e32 v56, v84, v84
	v_max_f32_e32 v57, v85, v85
	v_max_f32_e32 v58, v86, v86
	v_max_f32_e32 v59, v87, v87
	v_max_f32_e32 v56, 0, v56
	v_max_f32_e32 v57, 0, v57
	v_max_f32_e32 v58, 0, v58
	v_max_f32_e32 v59, 0, v59
	v_pk_mul_f32 v[56:57], v[56:57], v[56:57]
	v_pk_mul_f32 v[58:59], v[58:59], v[58:59]
	v_cvt_pk_bf16_f32 v56, v56, v57
	v_cvt_pk_bf16_f32 v57, v58, v59
	ds_write_b64 v70, v[56:57] offset:2048
	v_max_f32_e32 v56, v234, v234
	v_max_f32_e32 v57, v235, v235
	v_max_f32_e32 v58, v236, v236
	v_max_f32_e32 v59, v237, v237
	v_max_f32_e32 v56, 0, v56
	v_max_f32_e32 v57, 0, v57
	v_max_f32_e32 v58, 0, v58
	v_max_f32_e32 v59, 0, v59
	v_pk_mul_f32 v[56:57], v[56:57], v[56:57]
	v_pk_mul_f32 v[58:59], v[58:59], v[58:59]
	v_cvt_pk_bf16_f32 v56, v56, v57
	v_cvt_pk_bf16_f32 v57, v58, v59
	ds_write_b64 v71, v[56:57] offset:2048
	v_lshlrev_b64 v[56:57], 13, v[82:83]
	v_lshl_add_u64 v[56:57], s[0:1], 0, v[56:57]
	ds_read_b128 v[58:61], v80
	v_mfma_f32_16x16x32_bf16 v[40:43], v[174:177], v[212:215], v[64:67]
	v_lshl_add_u64 v[56:57], s[8:9], 1, v[56:57]
	v_lshl_add_u64 v[56:57], v[56:57], 0, v[122:123]
	v_lshl_add_u64 v[56:57], v[56:57], 0, v[124:125]
	ds_read_b128 v[62:65], v78
	v_lshl_add_u64 v[66:67], v[56:57], 0, v[126:127]
	s_waitcnt lgkmcnt(1)
	global_store_dwordx4 v[66:67], v[58:61], off nt
	v_lshl_add_u64 v[66:67], v[56:57], 0, v[128:129]
	ds_read_b128 v[58:61], v77
	s_waitcnt lgkmcnt(1)
	global_store_dwordx4 v[66:67], v[62:65], off nt
	ds_read_b128 v[62:65], v76
	v_lshl_add_u64 v[66:67], v[56:57], 0, v[130:131]
	v_max_f32_e32 v38, v38, v38
	s_waitcnt lgkmcnt(1)
	global_store_dwordx4 v[66:67], v[58:61], off nt
	v_max_f32_e32 v39, v39, v39
	v_max_f32_e32 v50, 0, v50
	v_lshl_add_u64 v[58:59], v[56:57], 0, v[132:133]
	s_waitcnt lgkmcnt(0)
	global_store_dwordx4 v[58:59], v[62:65], off nt
	v_max_f32_e32 v58, v238, v238
	v_max_f32_e32 v59, v239, v239
	v_max_f32_e32 v60, v240, v240
	v_max_f32_e32 v61, v241, v241
	v_max_f32_e32 v58, 0, v58
	v_max_f32_e32 v59, 0, v59
	v_max_f32_e32 v60, 0, v60
	v_max_f32_e32 v61, 0, v61
	v_pk_mul_f32 v[58:59], v[58:59], v[58:59]
	v_pk_mul_f32 v[60:61], v[60:61], v[60:61]
	v_cvt_pk_bf16_f32 v58, v58, v59
	v_cvt_pk_bf16_f32 v59, v60, v61
	ds_write_b64 v68, v[58:59]
	v_max_f32_e32 v58, v72, v72
	v_max_f32_e32 v59, v73, v73
	v_max_f32_e32 v60, v74, v74
	v_max_f32_e32 v61, v75, v75
	v_max_f32_e32 v58, 0, v58
	v_max_f32_e32 v59, 0, v59
	v_max_f32_e32 v60, 0, v60
	v_max_f32_e32 v61, 0, v61
	v_max_f32_e32 v51, 0, v51
	v_max_f32_e32 v36, 0, v36
	v_max_f32_e32 v37, 0, v37
	v_max_f32_e32 v38, 0, v38
	v_max_f32_e32 v39, 0, v39
	v_max_f32_e32 v32, v32, v32
	v_max_f32_e32 v33, v33, v33
	v_mfma_f32_16x16x32_bf16 v[28:31], v[134:137], v[216:219], v[28:31]
	v_mul_f32_e64 v58, v58, v58
	v_mul_f32_e64 v59, v59, v59
	v_pk_mul_f32 v[60:61], v[60:61], v[60:61]
	v_pk_mul_f32 v[52:53], v[52:53], v[52:53]
	v_mfma_f32_16x16x32_bf16 v[24:27], v[174:177], v[216:219], v[24:27]
	v_mul_f32_e64 v54, v54, v54
	v_mul_f32_e64 v55, v55, v55
	v_pk_mul_f32 v[48:49], v[48:49], v[48:49]
	v_pk_mul_f32 v[50:51], v[50:51], v[50:51]
	v_mfma_f32_16x16x32_bf16 v[20:23], v[96:99], v[216:219], v[20:23]
	v_mul_f32_e64 v36, v36, v36
	v_mul_f32_e64 v37, v37, v37
	v_pk_mul_f32 v[38:39], v[38:39], v[38:39]
	v_max_f32_e32 v32, 0, v32
	v_mfma_f32_16x16x32_bf16 v[16:19], v[178:181], v[216:219], v[16:19]
	v_max_f32_e32 v33, 0, v33
	v_max_f32_e32 v34, v34, v34
	v_max_f32_e32 v35, v35, v35
	v_mfma_f32_16x16x32_bf16 v[4:7], v[96:99], v[220:223], v[4:7]
	v_cvt_pk_bf16_f32 v58, v58, v59
	v_cvt_pk_bf16_f32 v59, v60, v61
	v_cvt_pk_bf16_f32 v52, v52, v53
	v_mfma_f32_16x16x32_bf16 v[0:3], v[178:181], v[220:223], v[0:3]
	v_cvt_pk_bf16_f32 v53, v54, v55
	v_cvt_pk_bf16_f32 v48, v48, v49
	v_cvt_pk_bf16_f32 v49, v50, v51
	v_cvt_pk_bf16_f32 v36, v36, v37
	v_cvt_pk_bf16_f32 v37, v38, v39
	v_max_f32_e32 v34, 0, v34
	v_max_f32_e32 v35, 0, v35
	v_pk_mul_f32 v[32:33], v[32:33], v[32:33]
	ds_write_b64 v69, v[58:59]
	ds_write_b64 v70, v[52:53]
	ds_write_b64 v71, v[48:49]
	v_max_f32_e32 v44, v44, v44
	v_max_f32_e32 v45, v45, v45
	v_max_f32_e32 v46, v46, v46
	v_max_f32_e32 v47, v47, v47
	ds_write_b64 v70, v[36:37] offset:2048
	v_cvt_pk_bf16_f32 v36, v32, v33
	v_pk_mul_f32 v[32:33], v[34:35], v[34:35]
	v_max_f32_e32 v44, 0, v44
	v_max_f32_e32 v45, 0, v45
	v_max_f32_e32 v46, 0, v46
	v_max_f32_e32 v47, 0, v47
	v_max_f32_e32 v40, v40, v40
	v_max_f32_e32 v41, v41, v41
	v_max_f32_e32 v42, v42, v42
	v_max_f32_e32 v43, v43, v43
	v_cvt_pk_bf16_f32 v37, v32, v33
	ds_read_b128 v[32:35], v80
	v_mfma_f32_16x16x32_bf16 v[12:15], v[134:137], v[220:223], v[12:15]
	v_mul_f32_e64 v44, v44, v44
	v_mul_f32_e64 v45, v45, v45
	v_pk_mul_f32 v[46:47], v[46:47], v[46:47]
	v_max_f32_e32 v40, 0, v40
	v_max_f32_e32 v41, 0, v41
	v_max_f32_e32 v42, 0, v42
	v_max_f32_e32 v43, 0, v43
	v_max_f32_e32 v28, v28, v28
	v_max_f32_e32 v29, v29, v29
	v_max_f32_e32 v30, v30, v30
	v_max_f32_e32 v31, v31, v31
	v_max_f32_e32 v24, v24, v24
	v_max_f32_e32 v25, v25, v25
	v_max_f32_e32 v26, v26, v26
	v_max_f32_e32 v27, v27, v27
	v_max_f32_e32 v20, v20, v20
	v_max_f32_e32 v21, v21, v21
	v_max_f32_e32 v22, v22, v22
	v_max_f32_e32 v23, v23, v23
	v_max_f32_e32 v16, v16, v16
	v_max_f32_e32 v17, v17, v17
	v_max_f32_e32 v18, v18, v18
	v_max_f32_e32 v19, v19, v19
	v_max_f32_e32 v4, v4, v4
	v_max_f32_e32 v5, v5, v5
	v_max_f32_e32 v6, v6, v6
	v_max_f32_e32 v7, v7, v7
	v_mfma_f32_16x16x32_bf16 v[8:11], v[174:177], v[220:223], v[8:11]
	v_cvt_pk_bf16_f32 v44, v44, v45
	v_cvt_pk_bf16_f32 v45, v46, v47
	v_pk_mul_f32 v[40:41], v[40:41], v[40:41]
	v_pk_mul_f32 v[42:43], v[42:43], v[42:43]
	s_mov_b64 s[0:1], 0x40000
	v_max_f32_e32 v28, 0, v28
	v_max_f32_e32 v29, 0, v29
	v_max_f32_e32 v30, 0, v30
	v_max_f32_e32 v31, 0, v31
	v_max_f32_e32 v24, 0, v24
	v_max_f32_e32 v25, 0, v25
	v_max_f32_e32 v26, 0, v26
	v_max_f32_e32 v27, 0, v27
	v_max_f32_e32 v20, 0, v20
	v_max_f32_e32 v21, 0, v21
	v_max_f32_e32 v22, 0, v22
	v_max_f32_e32 v23, 0, v23
	v_max_f32_e32 v16, 0, v16
	v_max_f32_e32 v17, 0, v17
	v_max_f32_e32 v18, 0, v18
	v_max_f32_e32 v19, 0, v19
	v_max_f32_e32 v4, 0, v4
	v_max_f32_e32 v5, 0, v5
	v_max_f32_e32 v6, 0, v6
	v_max_f32_e32 v7, 0, v7
	v_max_f32_e32 v0, v0, v0
	v_max_f32_e32 v1, v1, v1
	ds_write_b64 v68, v[44:45] offset:2048
	v_cvt_pk_bf16_f32 v40, v40, v41
	v_cvt_pk_bf16_f32 v41, v42, v43
	v_lshl_add_u64 v[44:45], v[56:57], 0, s[0:1]
	v_pk_mul_f32 v[28:29], v[28:29], v[28:29]
	v_pk_mul_f32 v[30:31], v[30:31], v[30:31]
	v_pk_mul_f32 v[24:25], v[24:25], v[24:25]
	v_pk_mul_f32 v[26:27], v[26:27], v[26:27]
	v_pk_mul_f32 v[20:21], v[20:21], v[20:21]
	v_pk_mul_f32 v[22:23], v[22:23], v[22:23]
	v_pk_mul_f32 v[16:17], v[16:17], v[16:17]
	v_pk_mul_f32 v[18:19], v[18:19], v[18:19]
	v_pk_mul_f32 v[4:5], v[4:5], v[4:5]
	v_pk_mul_f32 v[6:7], v[6:7], v[6:7]
	v_max_f32_e32 v0, 0, v0
	v_max_f32_e32 v1, 0, v1
	v_max_f32_e32 v2, v2, v2
	v_max_f32_e32 v3, v3, v3
	ds_write_b64 v69, v[40:41] offset:2048
	ds_write_b64 v71, v[36:37] offset:2048
	v_lshl_add_u64 v[40:41], v[44:45], 0, v[126:127]
	v_cvt_pk_bf16_f32 v28, v28, v29
	v_cvt_pk_bf16_f32 v29, v30, v31
	v_cvt_pk_bf16_f32 v24, v24, v25
	v_cvt_pk_bf16_f32 v25, v26, v27
	v_cvt_pk_bf16_f32 v20, v20, v21
	v_cvt_pk_bf16_f32 v21, v22, v23
	v_cvt_pk_bf16_f32 v16, v16, v17
	v_cvt_pk_bf16_f32 v17, v18, v19
	v_cvt_pk_bf16_f32 v4, v4, v5
	v_cvt_pk_bf16_f32 v5, v6, v7
	v_max_f32_e32 v2, 0, v2
	v_max_f32_e32 v3, 0, v3
	v_pk_mul_f32 v[0:1], v[0:1], v[0:1]
	ds_read_b128 v[36:39], v78
	s_waitcnt lgkmcnt(4)
	global_store_dwordx4 v[40:41], v[32:35], off nt
	ds_read_b128 v[32:35], v77
	ds_read_b128 v[40:43], v76
	ds_write_b64 v68, v[28:29]
	ds_write_b64 v69, v[24:25]
	ds_write_b64 v70, v[20:21]
	ds_write_b64 v71, v[16:17]
	v_max_f32_e32 v12, v12, v12
	v_max_f32_e32 v13, v13, v13
	v_max_f32_e32 v14, v14, v14
	v_max_f32_e32 v15, v15, v15
	ds_write_b64 v70, v[4:5] offset:2048
	v_cvt_pk_bf16_f32 v4, v0, v1
	v_pk_mul_f32 v[0:1], v[2:3], v[2:3]
	v_max_f32_e32 v12, 0, v12
	v_max_f32_e32 v13, 0, v13
	v_max_f32_e32 v14, 0, v14
	v_max_f32_e32 v15, 0, v15
	v_max_f32_e32 v8, v8, v8
	v_max_f32_e32 v9, v9, v9
	v_max_f32_e32 v10, v10, v10
	v_max_f32_e32 v11, v11, v11
	v_cvt_pk_bf16_f32 v5, v0, v1
	ds_read_b128 v[0:3], v80
	v_pk_mul_f32 v[12:13], v[12:13], v[12:13]
	v_pk_mul_f32 v[14:15], v[14:15], v[14:15]
	v_max_f32_e32 v8, 0, v8
	v_max_f32_e32 v9, 0, v9
	v_max_f32_e32 v10, 0, v10
	v_max_f32_e32 v11, 0, v11
	v_cvt_pk_bf16_f32 v12, v12, v13
	v_cvt_pk_bf16_f32 v13, v14, v15
	v_pk_mul_f32 v[8:9], v[8:9], v[8:9]
	v_pk_mul_f32 v[10:11], v[10:11], v[10:11]
	s_mov_b64 s[0:1], 0x80000
	ds_write_b64 v68, v[12:13] offset:2048
	v_cvt_pk_bf16_f32 v8, v8, v9
	v_cvt_pk_bf16_f32 v9, v10, v11
	v_lshl_add_u64 v[12:13], v[56:57], 0, s[0:1]
	ds_write_b64 v69, v[8:9] offset:2048
	ds_write_b64 v71, v[4:5] offset:2048
	v_lshl_add_u64 v[8:9], v[12:13], 0, v[126:127]
	ds_read_b128 v[4:7], v78
	s_waitcnt lgkmcnt(4)
	global_store_dwordx4 v[8:9], v[0:3], off nt
	ds_read_b128 v[0:3], v77
	ds_read_b128 v[8:11], v76
	v_lshl_add_u64 v[46:47], v[44:45], 0, v[128:129]
	v_lshl_add_u64 v[14:15], v[12:13], 0, v[128:129]
	global_store_dwordx4 v[46:47], v[36:39], off nt
	s_waitcnt lgkmcnt(2)
	global_store_dwordx4 v[14:15], v[4:7], off nt
	v_lshl_add_u64 v[36:37], v[44:45], 0, v[130:131]
	s_nop 0
	v_lshl_add_u64 v[4:5], v[12:13], 0, v[130:131]
	global_store_dwordx4 v[36:37], v[32:35], off nt
	s_waitcnt lgkmcnt(1)
	global_store_dwordx4 v[4:5], v[0:3], off nt
	v_lshl_add_u64 v[32:33], v[44:45], 0, v[132:133]
	s_nop 0
	v_lshl_add_u64 v[0:1], v[12:13], 0, v[132:133]
	global_store_dwordx4 v[32:33], v[40:43], off nt
	s_waitcnt lgkmcnt(0)
	global_store_dwordx4 v[0:1], v[8:11], off nt
	s_cmp_eq_u32 s21, s20
	s_mov_b64 s[8:9], s[6:7]
	s_cbranch_scc1 .LBB0_57

.LBB0_38:
	s_cmp_lg_u64 s[8:9], 0
	s_cselect_b32 s30, 1, 0
	s_mul_i32 s10, s10, 0xc0
	s_lshl_b32 s31, s11, 7
	s_mov_b32 s8, s31
	s_mov_b32 s9, 0
	v_readlane_b32 s26, v249, 3
	v_readlane_b32 s27, v249, 4
	s_lshl_b32 s0, s10, 11
	s_add_u32 s26, s26, s0
	s_addc_u32 s27, s27, 0
	s_lshl_b32 s0, s8, 11
	s_add_u32 s28, s4, s0
	s_addc_u32 s29, s5, 0
	v_lshrrev_b32_e32 v172, 6, v167
	v_and_b32_e32 v182, 15, v167
	v_bfe_u32 v183, v167, 4, 2
	v_readfirstlane_b32 s14, v172
	v_lshrrev_b32_e32 v243, 1, v182
	v_xor_b32_e32 v243, v243, v183
	v_lshlrev_b32_e32 v243, 4, v243
	v_lshl_add_u32 v243, v182, 7, v243
	v_lshrrev_b32_e32 v245, 1, v172
	v_mul_u32_u24_e32 v245, 0x3000, v245
	v_add_u32_e32 v242, v245, v243
	v_and_b32_e32 v245, 1, v172
	v_lshlrev_b32_e32 v245, 13, v245
	v_add_u32_e32 v244, v245, v243
	v_add_u32_e32 v244, 0x6000, v244
	v_xor_b32_e32 v243, 64, v242
	v_xor_b32_e32 v245, 64, v244
	v_lshrrev_b32_e32 v182, 3, v167
	v_bfe_u32 v183, v167, 4, 3
	v_and_b32_e32 v246, 7, v167
	v_xor_b32_e32 v246, v246, v183
	v_lshlrev_b32_e32 v246, 4, v246
	v_lshl_add_u32 v246, v182, 11, v246
	v_lshrrev_b32_e32 v182, 2, v167
	v_lshrrev_b32_e32 v183, 4, v167
	v_sub_u32_e32 v183, 0, v183
	v_xor_b32_e32 v183, v183, v167
	v_and_b32_e32 v183, 3, v183
	v_lshlrev_b32_e32 v224, 4, v183
	v_lshl_add_u32 v224, v182, 11, v224
	v_lshlrev_b32_e32 v225, 1, v140
	v_add_u32_e32 v225, 0xa000, v225
	v_lshlrev_b32_e32 v170, 1, v141
	v_add_u32_e32 v170, 0xa000, v170
	s_lshl_b32 s14, s14, 10
	s_mov_b64 s[16:17], s[26:27]
	s_mov_b64 s[18:19], s[28:29]
	s_cmp_lg_u32 s30, 0
	s_cbranch_scc1 .Lk64fc1_pre
	s_barrier
	s_add_u32 m0, s14, 0x0
	s_nop 0
	global_load_lds_dwordx4 v246, s[16:17]
	s_add_u32 m0, s14, 0x1000
	s_add_u32 s0, s16, 0x10000
	s_addc_u32 s1, s17, 0
	global_load_lds_dwordx4 v246, s[0:1]
	s_add_u32 m0, s14, 0x2000
	s_add_u32 s0, s16, 0x20000
	s_addc_u32 s1, s17, 0
	global_load_lds_dwordx4 v246, s[0:1]
	s_add_u32 m0, s14, 0x3000
	s_add_u32 s0, s16, 0x30000
	s_addc_u32 s1, s17, 0
	global_load_lds_dwordx4 v246, s[0:1]
	s_add_u32 m0, s14, 0x4000
	s_add_u32 s0, s16, 0x40000
	s_addc_u32 s1, s17, 0
	global_load_lds_dwordx4 v246, s[0:1]
	s_add_u32 m0, s14, 0x5000
	s_add_u32 s0, s16, 0x50000
	s_addc_u32 s1, s17, 0
	global_load_lds_dwordx4 v246, s[0:1]
	s_add_u32 m0, s14, 0x6000
	s_nop 0
	global_load_lds_dwordx4 v246, s[18:19]
	s_add_u32 m0, s14, 0x7000
	s_add_u32 s0, s18, 0x10000
	s_addc_u32 s1, s19, 0
	global_load_lds_dwordx4 v246, s[0:1]
	s_add_u32 m0, s14, 0x8000
	s_add_u32 s0, s18, 0x20000
	s_addc_u32 s1, s19, 0
	global_load_lds_dwordx4 v246, s[0:1]
	s_add_u32 m0, s14, 0x9000
	s_add_u32 s0, s18, 0x30000
	s_addc_u32 s1, s19, 0
	global_load_lds_dwordx4 v246, s[0:1]
.Lk64fc1_pre:
	s_add_u32 s16, s16, 0x80
	s_addc_u32 s17, s17, 0
	s_add_u32 s18, s18, 0x80
	s_addc_u32 s19, s19, 0
	v_mov_b32_e32 v96, 0
	v_mov_b32_e32 v97, 0
	v_mov_b32_e32 v98, 0
	v_mov_b32_e32 v99, 0
	v_mov_b32_e32 v108, 0
	v_mov_b32_e32 v109, 0
	v_mov_b32_e32 v110, 0
	v_mov_b32_e32 v111, 0
	v_mov_b32_e32 v104, 0
	v_mov_b32_e32 v105, 0
	v_mov_b32_e32 v106, 0
	v_mov_b32_e32 v107, 0
	v_mov_b32_e32 v100, 0
	v_mov_b32_e32 v101, 0
	v_mov_b32_e32 v102, 0
	v_mov_b32_e32 v103, 0
	v_mov_b32_e32 v92, 0
	v_mov_b32_e32 v93, 0
	v_mov_b32_e32 v94, 0
	v_mov_b32_e32 v95, 0
	v_mov_b32_e32 v88, 0
	v_mov_b32_e32 v89, 0
	v_mov_b32_e32 v90, 0
	v_mov_b32_e32 v91, 0
	v_mov_b32_e32 v84, 0
	v_mov_b32_e32 v85, 0
	v_mov_b32_e32 v86, 0
	v_mov_b32_e32 v87, 0
	v_mov_b32_e32 v80, 0
	v_mov_b32_e32 v81, 0
	v_mov_b32_e32 v82, 0
	v_mov_b32_e32 v83, 0
	v_mov_b32_e32 v76, 0
	v_mov_b32_e32 v77, 0
	v_mov_b32_e32 v78, 0
	v_mov_b32_e32 v79, 0
	v_mov_b32_e32 v72, 0
	v_mov_b32_e32 v73, 0
	v_mov_b32_e32 v74, 0
	v_mov_b32_e32 v75, 0
	v_mov_b32_e32 v52, 0
	v_mov_b32_e32 v53, 0
	v_mov_b32_e32 v54, 0
	v_mov_b32_e32 v55, 0
	v_mov_b32_e32 v48, 0
	v_mov_b32_e32 v49, 0
	v_mov_b32_e32 v50, 0
	v_mov_b32_e32 v51, 0
	v_mov_b32_e32 v68, 0
	v_mov_b32_e32 v69, 0
	v_mov_b32_e32 v70, 0
	v_mov_b32_e32 v71, 0
	v_mov_b32_e32 v64, 0
	v_mov_b32_e32 v65, 0
	v_mov_b32_e32 v66, 0
	v_mov_b32_e32 v67, 0
	v_mov_b32_e32 v60, 0
	v_mov_b32_e32 v61, 0
	v_mov_b32_e32 v62, 0
	v_mov_b32_e32 v63, 0
	v_mov_b32_e32 v56, 0
	v_mov_b32_e32 v57, 0
	v_mov_b32_e32 v58, 0
	v_mov_b32_e32 v59, 0
	v_mov_b32_e32 v28, 0
	v_mov_b32_e32 v29, 0
	v_mov_b32_e32 v30, 0
	v_mov_b32_e32 v31, 0
	v_mov_b32_e32 v24, 0
	v_mov_b32_e32 v25, 0
	v_mov_b32_e32 v26, 0
	v_mov_b32_e32 v27, 0
	v_mov_b32_e32 v20, 0
	v_mov_b32_e32 v21, 0
	v_mov_b32_e32 v22, 0
	v_mov_b32_e32 v23, 0
	v_mov_b32_e32 v16, 0
	v_mov_b32_e32 v17, 0
	v_mov_b32_e32 v18, 0
	v_mov_b32_e32 v19, 0
	v_mov_b32_e32 v12, 0
	v_mov_b32_e32 v13, 0
	v_mov_b32_e32 v14, 0
	v_mov_b32_e32 v15, 0
	v_mov_b32_e32 v8, 0
	v_mov_b32_e32 v9, 0
	v_mov_b32_e32 v10, 0
	v_mov_b32_e32 v11, 0
	v_mov_b32_e32 v4, 0
	v_mov_b32_e32 v5, 0
	v_mov_b32_e32 v6, 0
	v_mov_b32_e32 v7, 0
	v_mov_b32_e32 v0, 0
	v_mov_b32_e32 v1, 0
	v_mov_b32_e32 v2, 0
	v_mov_b32_e32 v3, 0
	s_mov_b32 s22, 7
.Lk64fc1_loop:
	s_waitcnt vmcnt(0)
	s_barrier
	s_add_u32 m0, s14, 0xa000
	s_nop 0
	global_load_lds_dwordx4 v246, s[16:17]
	s_add_u32 m0, s14, 0xb000
	s_add_u32 s0, s16, 0x10000
	s_addc_u32 s1, s17, 0
	global_load_lds_dwordx4 v246, s[0:1]
	s_add_u32 m0, s14, 0xc000
	s_add_u32 s0, s16, 0x20000
	s_addc_u32 s1, s17, 0
	global_load_lds_dwordx4 v246, s[0:1]
	s_add_u32 m0, s14, 0xd000
	s_add_u32 s0, s16, 0x30000
	s_addc_u32 s1, s17, 0
	global_load_lds_dwordx4 v246, s[0:1]
	s_add_u32 m0, s14, 0xe000
	s_add_u32 s0, s16, 0x40000
	s_addc_u32 s1, s17, 0
	global_load_lds_dwordx4 v246, s[0:1]
	s_add_u32 m0, s14, 0xf000
	s_add_u32 s0, s16, 0x50000
	s_addc_u32 s1, s17, 0
	global_load_lds_dwordx4 v246, s[0:1]
	s_add_u32 m0, s14, 0x10000
	s_nop 0
	global_load_lds_dwordx4 v246, s[18:19]
	s_add_u32 m0, s14, 0x11000
	s_add_u32 s0, s18, 0x10000
	s_addc_u32 s1, s19, 0
	global_load_lds_dwordx4 v246, s[0:1]
	s_add_u32 m0, s14, 0x12000
	s_add_u32 s0, s18, 0x20000
	s_addc_u32 s1, s19, 0
	global_load_lds_dwordx4 v246, s[0:1]
	s_add_u32 m0, s14, 0x13000
	s_add_u32 s0, s18, 0x30000
	s_addc_u32 s1, s19, 0
	global_load_lds_dwordx4 v246, s[0:1]
	s_add_u32 s16, s16, 0x80
	s_addc_u32 s17, s17, 0
	s_add_u32 s18, s18, 0x80
	s_addc_u32 s19, s19, 0
	ds_read_b128 v[178:181], v244 offset:0
	ds_read_b128 v[212:215], v244 offset:2048
	ds_read_b128 v[216:219], v244 offset:4096
	ds_read_b128 v[220:223], v244 offset:6144
	ds_read_b128 v[32:35], v242 offset:0
	ds_read_b128 v[36:39], v242 offset:2048
	ds_read_b128 v[40:43], v242 offset:4096
	ds_read_b128 v[44:47], v242 offset:6144
	ds_read_b128 v[134:137], v242 offset:8192
	ds_read_b128 v[174:177], v242 offset:10240
	s_waitcnt lgkmcnt(5)
	v_mfma_f32_16x16x32_bf16 v[96:99], v[178:181], v[32:35], v[96:99]
	v_mfma_f32_16x16x32_bf16 v[108:111], v[212:215], v[32:35], v[108:111]
	v_mfma_f32_16x16x32_bf16 v[104:107], v[216:219], v[32:35], v[104:107]
	v_mfma_f32_16x16x32_bf16 v[100:103], v[220:223], v[32:35], v[100:103]
	s_waitcnt lgkmcnt(4)
	v_mfma_f32_16x16x32_bf16 v[92:95], v[178:181], v[36:39], v[92:95]
	v_mfma_f32_16x16x32_bf16 v[88:91], v[212:215], v[36:39], v[88:91]
	v_mfma_f32_16x16x32_bf16 v[84:87], v[216:219], v[36:39], v[84:87]
	v_mfma_f32_16x16x32_bf16 v[80:83], v[220:223], v[36:39], v[80:83]
	s_waitcnt lgkmcnt(3)
	v_mfma_f32_16x16x32_bf16 v[76:79], v[178:181], v[40:43], v[76:79]
	v_mfma_f32_16x16x32_bf16 v[72:75], v[212:215], v[40:43], v[72:75]
	v_mfma_f32_16x16x32_bf16 v[52:55], v[216:219], v[40:43], v[52:55]
	v_mfma_f32_16x16x32_bf16 v[48:51], v[220:223], v[40:43], v[48:51]
	s_waitcnt lgkmcnt(2)
	v_mfma_f32_16x16x32_bf16 v[68:71], v[178:181], v[44:47], v[68:71]
	v_mfma_f32_16x16x32_bf16 v[64:67], v[212:215], v[44:47], v[64:67]
	v_mfma_f32_16x16x32_bf16 v[60:63], v[216:219], v[44:47], v[60:63]
	v_mfma_f32_16x16x32_bf16 v[56:59], v[220:223], v[44:47], v[56:59]
	s_waitcnt lgkmcnt(1)
	v_mfma_f32_16x16x32_bf16 v[28:31], v[178:181], v[134:137], v[28:31]
	v_mfma_f32_16x16x32_bf16 v[24:27], v[212:215], v[134:137], v[24:27]
	v_mfma_f32_16x16x32_bf16 v[20:23], v[216:219], v[134:137], v[20:23]
	v_mfma_f32_16x16x32_bf16 v[16:19], v[220:223], v[134:137], v[16:19]
	s_waitcnt lgkmcnt(0)
	v_mfma_f32_16x16x32_bf16 v[12:15], v[178:181], v[174:177], v[12:15]
	v_mfma_f32_16x16x32_bf16 v[8:11], v[212:215], v[174:177], v[8:11]
	v_mfma_f32_16x16x32_bf16 v[4:7], v[216:219], v[174:177], v[4:7]
	v_mfma_f32_16x16x32_bf16 v[0:3], v[220:223], v[174:177], v[0:3]
	ds_read_b128 v[178:181], v245 offset:0
	ds_read_b128 v[212:215], v245 offset:2048
	ds_read_b128 v[216:219], v245 offset:4096
	ds_read_b128 v[220:223], v245 offset:6144
	ds_read_b128 v[32:35], v243 offset:0
	ds_read_b128 v[36:39], v243 offset:2048
	ds_read_b128 v[40:43], v243 offset:4096
	ds_read_b128 v[44:47], v243 offset:6144
	ds_read_b128 v[134:137], v243 offset:8192
	ds_read_b128 v[174:177], v243 offset:10240
	s_waitcnt lgkmcnt(5)
	v_mfma_f32_16x16x32_bf16 v[96:99], v[178:181], v[32:35], v[96:99]
	v_mfma_f32_16x16x32_bf16 v[108:111], v[212:215], v[32:35], v[108:111]
	v_mfma_f32_16x16x32_bf16 v[104:107], v[216:219], v[32:35], v[104:107]
	v_mfma_f32_16x16x32_bf16 v[100:103], v[220:223], v[32:35], v[100:103]
	s_waitcnt lgkmcnt(4)
	v_mfma_f32_16x16x32_bf16 v[92:95], v[178:181], v[36:39], v[92:95]
	v_mfma_f32_16x16x32_bf16 v[88:91], v[212:215], v[36:39], v[88:91]
	v_mfma_f32_16x16x32_bf16 v[84:87], v[216:219], v[36:39], v[84:87]
	v_mfma_f32_16x16x32_bf16 v[80:83], v[220:223], v[36:39], v[80:83]
	s_waitcnt lgkmcnt(3)
	v_mfma_f32_16x16x32_bf16 v[76:79], v[178:181], v[40:43], v[76:79]
	v_mfma_f32_16x16x32_bf16 v[72:75], v[212:215], v[40:43], v[72:75]
	v_mfma_f32_16x16x32_bf16 v[52:55], v[216:219], v[40:43], v[52:55]
	v_mfma_f32_16x16x32_bf16 v[48:51], v[220:223], v[40:43], v[48:51]
	s_waitcnt lgkmcnt(2)
	v_mfma_f32_16x16x32_bf16 v[68:71], v[178:181], v[44:47], v[68:71]
	v_mfma_f32_16x16x32_bf16 v[64:67], v[212:215], v[44:47], v[64:67]
	v_mfma_f32_16x16x32_bf16 v[60:63], v[216:219], v[44:47], v[60:63]
	v_mfma_f32_16x16x32_bf16 v[56:59], v[220:223], v[44:47], v[56:59]
	s_waitcnt lgkmcnt(1)
	v_mfma_f32_16x16x32_bf16 v[28:31], v[178:181], v[134:137], v[28:31]
	v_mfma_f32_16x16x32_bf16 v[24:27], v[212:215], v[134:137], v[24:27]
	v_mfma_f32_16x16x32_bf16 v[20:23], v[216:219], v[134:137], v[20:23]
	v_mfma_f32_16x16x32_bf16 v[16:19], v[220:223], v[134:137], v[16:19]
	s_waitcnt lgkmcnt(0)
	v_mfma_f32_16x16x32_bf16 v[12:15], v[178:181], v[174:177], v[12:15]
	v_mfma_f32_16x16x32_bf16 v[8:11], v[212:215], v[174:177], v[8:11]
	v_mfma_f32_16x16x32_bf16 v[4:7], v[216:219], v[174:177], v[4:7]
	v_mfma_f32_16x16x32_bf16 v[0:3], v[220:223], v[174:177], v[0:3]
	s_waitcnt vmcnt(0)
	s_barrier
	s_add_u32 m0, s14, 0x0
	s_nop 0
	global_load_lds_dwordx4 v246, s[16:17]
	s_add_u32 m0, s14, 0x1000
	s_add_u32 s0, s16, 0x10000
	s_addc_u32 s1, s17, 0
	global_load_lds_dwordx4 v246, s[0:1]
	s_add_u32 m0, s14, 0x2000
	s_add_u32 s0, s16, 0x20000
	s_addc_u32 s1, s17, 0
	global_load_lds_dwordx4 v246, s[0:1]
	s_add_u32 m0, s14, 0x3000
	s_add_u32 s0, s16, 0x30000
	s_addc_u32 s1, s17, 0
	global_load_lds_dwordx4 v246, s[0:1]
	s_add_u32 m0, s14, 0x4000
	s_add_u32 s0, s16, 0x40000
	s_addc_u32 s1, s17, 0
	global_load_lds_dwordx4 v246, s[0:1]
	s_add_u32 m0, s14, 0x5000
	s_add_u32 s0, s16, 0x50000
	s_addc_u32 s1, s17, 0
	global_load_lds_dwordx4 v246, s[0:1]
	s_add_u32 m0, s14, 0x6000
	s_nop 0
	global_load_lds_dwordx4 v246, s[18:19]
	s_add_u32 m0, s14, 0x7000
	s_add_u32 s0, s18, 0x10000
	s_addc_u32 s1, s19, 0
	global_load_lds_dwordx4 v246, s[0:1]
	s_add_u32 m0, s14, 0x8000
	s_add_u32 s0, s18, 0x20000
	s_addc_u32 s1, s19, 0
	global_load_lds_dwordx4 v246, s[0:1]
	s_add_u32 m0, s14, 0x9000
	s_add_u32 s0, s18, 0x30000
	s_addc_u32 s1, s19, 0
	global_load_lds_dwordx4 v246, s[0:1]
	s_add_u32 s16, s16, 0x80
	s_addc_u32 s17, s17, 0
	s_add_u32 s18, s18, 0x80
	s_addc_u32 s19, s19, 0
	ds_read_b128 v[178:181], v244 offset:40960
	ds_read_b128 v[212:215], v244 offset:43008
	ds_read_b128 v[216:219], v244 offset:45056
	ds_read_b128 v[220:223], v244 offset:47104
	ds_read_b128 v[32:35], v242 offset:40960
	ds_read_b128 v[36:39], v242 offset:43008
	ds_read_b128 v[40:43], v242 offset:45056
	ds_read_b128 v[44:47], v242 offset:47104
	ds_read_b128 v[134:137], v242 offset:49152
	ds_read_b128 v[174:177], v242 offset:51200
	s_waitcnt lgkmcnt(5)
	v_mfma_f32_16x16x32_bf16 v[96:99], v[178:181], v[32:35], v[96:99]
	v_mfma_f32_16x16x32_bf16 v[108:111], v[212:215], v[32:35], v[108:111]
	v_mfma_f32_16x16x32_bf16 v[104:107], v[216:219], v[32:35], v[104:107]
	v_mfma_f32_16x16x32_bf16 v[100:103], v[220:223], v[32:35], v[100:103]
	s_waitcnt lgkmcnt(4)
	v_mfma_f32_16x16x32_bf16 v[92:95], v[178:181], v[36:39], v[92:95]
	v_mfma_f32_16x16x32_bf16 v[88:91], v[212:215], v[36:39], v[88:91]
	v_mfma_f32_16x16x32_bf16 v[84:87], v[216:219], v[36:39], v[84:87]
	v_mfma_f32_16x16x32_bf16 v[80:83], v[220:223], v[36:39], v[80:83]
	s_waitcnt lgkmcnt(3)
	v_mfma_f32_16x16x32_bf16 v[76:79], v[178:181], v[40:43], v[76:79]
	v_mfma_f32_16x16x32_bf16 v[72:75], v[212:215], v[40:43], v[72:75]
	v_mfma_f32_16x16x32_bf16 v[52:55], v[216:219], v[40:43], v[52:55]
	v_mfma_f32_16x16x32_bf16 v[48:51], v[220:223], v[40:43], v[48:51]
	s_waitcnt lgkmcnt(2)
	v_mfma_f32_16x16x32_bf16 v[68:71], v[178:181], v[44:47], v[68:71]
	v_mfma_f32_16x16x32_bf16 v[64:67], v[212:215], v[44:47], v[64:67]
	v_mfma_f32_16x16x32_bf16 v[60:63], v[216:219], v[44:47], v[60:63]
	v_mfma_f32_16x16x32_bf16 v[56:59], v[220:223], v[44:47], v[56:59]
	s_waitcnt lgkmcnt(1)
	v_mfma_f32_16x16x32_bf16 v[28:31], v[178:181], v[134:137], v[28:31]
	v_mfma_f32_16x16x32_bf16 v[24:27], v[212:215], v[134:137], v[24:27]
	v_mfma_f32_16x16x32_bf16 v[20:23], v[216:219], v[134:137], v[20:23]
	v_mfma_f32_16x16x32_bf16 v[16:19], v[220:223], v[134:137], v[16:19]
	s_waitcnt lgkmcnt(0)
	v_mfma_f32_16x16x32_bf16 v[12:15], v[178:181], v[174:177], v[12:15]
	v_mfma_f32_16x16x32_bf16 v[8:11], v[212:215], v[174:177], v[8:11]
	v_mfma_f32_16x16x32_bf16 v[4:7], v[216:219], v[174:177], v[4:7]
	v_mfma_f32_16x16x32_bf16 v[0:3], v[220:223], v[174:177], v[0:3]
	ds_read_b128 v[178:181], v245 offset:40960
	ds_read_b128 v[212:215], v245 offset:43008
	ds_read_b128 v[216:219], v245 offset:45056
	ds_read_b128 v[220:223], v245 offset:47104
	ds_read_b128 v[32:35], v243 offset:40960
	ds_read_b128 v[36:39], v243 offset:43008
	ds_read_b128 v[40:43], v243 offset:45056
	ds_read_b128 v[44:47], v243 offset:47104
	ds_read_b128 v[134:137], v243 offset:49152
	ds_read_b128 v[174:177], v243 offset:51200
	s_waitcnt lgkmcnt(5)
	v_mfma_f32_16x16x32_bf16 v[96:99], v[178:181], v[32:35], v[96:99]
	v_mfma_f32_16x16x32_bf16 v[108:111], v[212:215], v[32:35], v[108:111]
	v_mfma_f32_16x16x32_bf16 v[104:107], v[216:219], v[32:35], v[104:107]
	v_mfma_f32_16x16x32_bf16 v[100:103], v[220:223], v[32:35], v[100:103]
	s_waitcnt lgkmcnt(4)
	v_mfma_f32_16x16x32_bf16 v[92:95], v[178:181], v[36:39], v[92:95]
	v_mfma_f32_16x16x32_bf16 v[88:91], v[212:215], v[36:39], v[88:91]
	v_mfma_f32_16x16x32_bf16 v[84:87], v[216:219], v[36:39], v[84:87]
	v_mfma_f32_16x16x32_bf16 v[80:83], v[220:223], v[36:39], v[80:83]
	s_waitcnt lgkmcnt(3)
	v_mfma_f32_16x16x32_bf16 v[76:79], v[178:181], v[40:43], v[76:79]
	v_mfma_f32_16x16x32_bf16 v[72:75], v[212:215], v[40:43], v[72:75]
	v_mfma_f32_16x16x32_bf16 v[52:55], v[216:219], v[40:43], v[52:55]
	v_mfma_f32_16x16x32_bf16 v[48:51], v[220:223], v[40:43], v[48:51]
	s_waitcnt lgkmcnt(2)
	v_mfma_f32_16x16x32_bf16 v[68:71], v[178:181], v[44:47], v[68:71]
	v_mfma_f32_16x16x32_bf16 v[64:67], v[212:215], v[44:47], v[64:67]
	v_mfma_f32_16x16x32_bf16 v[60:63], v[216:219], v[44:47], v[60:63]
	v_mfma_f32_16x16x32_bf16 v[56:59], v[220:223], v[44:47], v[56:59]
	s_waitcnt lgkmcnt(1)
	v_mfma_f32_16x16x32_bf16 v[28:31], v[178:181], v[134:137], v[28:31]
	v_mfma_f32_16x16x32_bf16 v[24:27], v[212:215], v[134:137], v[24:27]
	v_mfma_f32_16x16x32_bf16 v[20:23], v[216:219], v[134:137], v[20:23]
	v_mfma_f32_16x16x32_bf16 v[16:19], v[220:223], v[134:137], v[16:19]
	s_waitcnt lgkmcnt(0)
	v_mfma_f32_16x16x32_bf16 v[12:15], v[178:181], v[174:177], v[12:15]
	v_mfma_f32_16x16x32_bf16 v[8:11], v[212:215], v[174:177], v[8:11]
	v_mfma_f32_16x16x32_bf16 v[4:7], v[216:219], v[174:177], v[4:7]
	v_mfma_f32_16x16x32_bf16 v[0:3], v[220:223], v[174:177], v[0:3]
	s_sub_u32 s22, s22, 1
	s_cmp_lg_u32 s22, 0
	s_cbranch_scc1 .Lk64fc1_loop
	s_waitcnt vmcnt(0)
	s_barrier
	s_add_u32 m0, s14, 0xa000
	s_add_u32 s0, s26, 0x780
	s_addc_u32 s1, s27, 0
	global_load_lds_dwordx4 v224, s[0:1]
	s_add_u32 m0, s14, 0xb000
	s_add_u32 s0, s26, 0x20780
	s_addc_u32 s1, s27, 0
	global_load_lds_dwordx4 v224, s[0:1]
	s_add_u32 m0, s14, 0xc000
	s_add_u32 s0, s26, 0x40780
	s_addc_u32 s1, s27, 0
	global_load_lds_dwordx4 v224, s[0:1]
	s_add_u32 m0, s14, 0xd000
	s_add_u32 s0, s28, 0x780
	s_addc_u32 s1, s29, 0
	global_load_lds_dwordx4 v224, s[0:1]
	s_add_u32 m0, s14, 0xe000
	s_add_u32 s0, s28, 0x20780
	s_addc_u32 s1, s29, 0
	global_load_lds_dwordx4 v224, s[0:1]
	s_add_u32 m0, s14, 0xf000
	s_add_u32 s0, s26, 0x7c0
	s_addc_u32 s1, s27, 0
	global_load_lds_dwordx4 v224, s[0:1]
	s_add_u32 m0, s14, 0x10000
	s_add_u32 s0, s26, 0x207c0
	s_addc_u32 s1, s27, 0
	global_load_lds_dwordx4 v224, s[0:1]
	s_add_u32 m0, s14, 0x11000
	s_add_u32 s0, s26, 0x407c0
	s_addc_u32 s1, s27, 0
	global_load_lds_dwordx4 v224, s[0:1]
	s_add_u32 m0, s14, 0x12000
	s_add_u32 s0, s28, 0x7c0
	s_addc_u32 s1, s29, 0
	global_load_lds_dwordx4 v224, s[0:1]
	s_add_u32 m0, s14, 0x13000
	s_add_u32 s0, s28, 0x207c0
	s_addc_u32 s1, s29, 0
	global_load_lds_dwordx4 v224, s[0:1]
	ds_read_b128 v[178:181], v244 offset:0
	ds_read_b128 v[212:215], v244 offset:2048
	ds_read_b128 v[216:219], v244 offset:4096
	ds_read_b128 v[220:223], v244 offset:6144
	ds_read_b128 v[32:35], v242 offset:0
	ds_read_b128 v[36:39], v242 offset:2048
	ds_read_b128 v[40:43], v242 offset:4096
	ds_read_b128 v[44:47], v242 offset:6144
	ds_read_b128 v[134:137], v242 offset:8192
	ds_read_b128 v[174:177], v242 offset:10240
	s_waitcnt lgkmcnt(5)
	v_mfma_f32_16x16x32_bf16 v[96:99], v[178:181], v[32:35], v[96:99]
	v_mfma_f32_16x16x32_bf16 v[108:111], v[212:215], v[32:35], v[108:111]
	v_mfma_f32_16x16x32_bf16 v[104:107], v[216:219], v[32:35], v[104:107]
	v_mfma_f32_16x16x32_bf16 v[100:103], v[220:223], v[32:35], v[100:103]
	s_waitcnt lgkmcnt(4)
	v_mfma_f32_16x16x32_bf16 v[92:95], v[178:181], v[36:39], v[92:95]
	v_mfma_f32_16x16x32_bf16 v[88:91], v[212:215], v[36:39], v[88:91]
	v_mfma_f32_16x16x32_bf16 v[84:87], v[216:219], v[36:39], v[84:87]
	v_mfma_f32_16x16x32_bf16 v[80:83], v[220:223], v[36:39], v[80:83]
	s_waitcnt lgkmcnt(3)
	v_mfma_f32_16x16x32_bf16 v[76:79], v[178:181], v[40:43], v[76:79]
	v_mfma_f32_16x16x32_bf16 v[72:75], v[212:215], v[40:43], v[72:75]
	v_mfma_f32_16x16x32_bf16 v[52:55], v[216:219], v[40:43], v[52:55]
	v_mfma_f32_16x16x32_bf16 v[48:51], v[220:223], v[40:43], v[48:51]
	s_waitcnt lgkmcnt(2)
	v_mfma_f32_16x16x32_bf16 v[68:71], v[178:181], v[44:47], v[68:71]
	v_mfma_f32_16x16x32_bf16 v[64:67], v[212:215], v[44:47], v[64:67]
	v_mfma_f32_16x16x32_bf16 v[60:63], v[216:219], v[44:47], v[60:63]
	v_mfma_f32_16x16x32_bf16 v[56:59], v[220:223], v[44:47], v[56:59]
	s_waitcnt lgkmcnt(1)
	v_mfma_f32_16x16x32_bf16 v[28:31], v[178:181], v[134:137], v[28:31]
	v_mfma_f32_16x16x32_bf16 v[24:27], v[212:215], v[134:137], v[24:27]
	v_mfma_f32_16x16x32_bf16 v[20:23], v[216:219], v[134:137], v[20:23]
	v_mfma_f32_16x16x32_bf16 v[16:19], v[220:223], v[134:137], v[16:19]
	s_waitcnt lgkmcnt(0)
	v_mfma_f32_16x16x32_bf16 v[12:15], v[178:181], v[174:177], v[12:15]
	v_mfma_f32_16x16x32_bf16 v[8:11], v[212:215], v[174:177], v[8:11]
	v_mfma_f32_16x16x32_bf16 v[4:7], v[216:219], v[174:177], v[4:7]
	v_mfma_f32_16x16x32_bf16 v[0:3], v[220:223], v[174:177], v[0:3]
	ds_read_b128 v[178:181], v245 offset:0
	ds_read_b128 v[212:215], v245 offset:2048
	ds_read_b128 v[216:219], v245 offset:4096
	ds_read_b128 v[220:223], v245 offset:6144
	ds_read_b128 v[32:35], v243 offset:0
	ds_read_b128 v[36:39], v243 offset:2048
	ds_read_b128 v[40:43], v243 offset:4096
	ds_read_b128 v[44:47], v243 offset:6144
	ds_read_b128 v[134:137], v243 offset:8192
	ds_read_b128 v[174:177], v243 offset:10240
	s_waitcnt lgkmcnt(5)
	v_mfma_f32_16x16x32_bf16 v[96:99], v[178:181], v[32:35], v[96:99]
	v_mfma_f32_16x16x32_bf16 v[108:111], v[212:215], v[32:35], v[108:111]
	v_mfma_f32_16x16x32_bf16 v[104:107], v[216:219], v[32:35], v[104:107]
	v_mfma_f32_16x16x32_bf16 v[100:103], v[220:223], v[32:35], v[100:103]
	s_waitcnt lgkmcnt(4)
	v_mfma_f32_16x16x32_bf16 v[92:95], v[178:181], v[36:39], v[92:95]
	v_mfma_f32_16x16x32_bf16 v[88:91], v[212:215], v[36:39], v[88:91]
	v_mfma_f32_16x16x32_bf16 v[84:87], v[216:219], v[36:39], v[84:87]
	v_mfma_f32_16x16x32_bf16 v[80:83], v[220:223], v[36:39], v[80:83]
	s_waitcnt lgkmcnt(3)
	v_mfma_f32_16x16x32_bf16 v[76:79], v[178:181], v[40:43], v[76:79]
	v_mfma_f32_16x16x32_bf16 v[72:75], v[212:215], v[40:43], v[72:75]
	v_mfma_f32_16x16x32_bf16 v[52:55], v[216:219], v[40:43], v[52:55]
	v_mfma_f32_16x16x32_bf16 v[48:51], v[220:223], v[40:43], v[48:51]
	s_waitcnt lgkmcnt(2)
	v_mfma_f32_16x16x32_bf16 v[68:71], v[178:181], v[44:47], v[68:71]
	v_mfma_f32_16x16x32_bf16 v[64:67], v[212:215], v[44:47], v[64:67]
	v_mfma_f32_16x16x32_bf16 v[60:63], v[216:219], v[44:47], v[60:63]
	v_mfma_f32_16x16x32_bf16 v[56:59], v[220:223], v[44:47], v[56:59]
	s_waitcnt lgkmcnt(1)
	v_mfma_f32_16x16x32_bf16 v[28:31], v[178:181], v[134:137], v[28:31]
	v_mfma_f32_16x16x32_bf16 v[24:27], v[212:215], v[134:137], v[24:27]
	v_mfma_f32_16x16x32_bf16 v[20:23], v[216:219], v[134:137], v[20:23]
	v_mfma_f32_16x16x32_bf16 v[16:19], v[220:223], v[134:137], v[16:19]
	s_waitcnt lgkmcnt(0)
	v_mfma_f32_16x16x32_bf16 v[12:15], v[178:181], v[174:177], v[12:15]
	v_mfma_f32_16x16x32_bf16 v[8:11], v[212:215], v[174:177], v[8:11]
	v_mfma_f32_16x16x32_bf16 v[4:7], v[216:219], v[174:177], v[4:7]
	v_mfma_f32_16x16x32_bf16 v[0:3], v[220:223], v[174:177], v[0:3]
	s_waitcnt vmcnt(0)
	s_barrier
	s_cmp_lg_u64 s[6:7], 0
	s_cbranch_scc0 .Lk64fc1_nonext
	s_mul_i32 s0, s24, 0x60000
	v_readlane_b32 s16, v249, 3
	v_readlane_b32 s17, v249, 4
	s_add_u32 s16, s16, s0
	s_addc_u32 s17, s17, 0
	s_lshl_b32 s0, s23, 18
	s_add_u32 s18, s4, s0
	s_addc_u32 s19, s5, 0
	s_add_u32 m0, s14, 0x0
	s_nop 0
	global_load_lds_dwordx4 v246, s[16:17]
	s_add_u32 m0, s14, 0x1000
	s_add_u32 s0, s16, 0x10000
	s_addc_u32 s1, s17, 0
	global_load_lds_dwordx4 v246, s[0:1]
	s_add_u32 m0, s14, 0x2000
	s_add_u32 s0, s16, 0x20000
	s_addc_u32 s1, s17, 0
	global_load_lds_dwordx4 v246, s[0:1]
	s_add_u32 m0, s14, 0x3000
	s_add_u32 s0, s16, 0x30000
	s_addc_u32 s1, s17, 0
	global_load_lds_dwordx4 v246, s[0:1]
	s_add_u32 m0, s14, 0x4000
	s_add_u32 s0, s16, 0x40000
	s_addc_u32 s1, s17, 0
	global_load_lds_dwordx4 v246, s[0:1]
	s_add_u32 m0, s14, 0x5000
	s_add_u32 s0, s16, 0x50000
	s_addc_u32 s1, s17, 0
	global_load_lds_dwordx4 v246, s[0:1]
	s_add_u32 m0, s14, 0x6000
	s_nop 0
	global_load_lds_dwordx4 v246, s[18:19]
	s_add_u32 m0, s14, 0x7000
	s_add_u32 s0, s18, 0x10000
	s_addc_u32 s1, s19, 0
	global_load_lds_dwordx4 v246, s[0:1]
	s_add_u32 m0, s14, 0x8000
	s_add_u32 s0, s18, 0x20000
	s_addc_u32 s1, s19, 0
	global_load_lds_dwordx4 v246, s[0:1]
	s_add_u32 m0, s14, 0x9000
	s_add_u32 s0, s18, 0x30000
	s_addc_u32 s1, s19, 0
	global_load_lds_dwordx4 v246, s[0:1]
.Lk64fc1_nonext:
	ds_read_b128 v[178:181], v170 offset:12288
	ds_read_b128 v[212:215], v170 offset:13312
	ds_read_b128 v[216:219], v170 offset:14336
	ds_read_b128 v[220:223], v170 offset:15360
	ds_read_b128 v[32:35], v225 offset:0
	ds_read_b128 v[36:39], v225 offset:1024
	ds_read_b128 v[40:43], v225 offset:2048
	ds_read_b128 v[44:47], v225 offset:3072
	ds_read_b128 v[134:137], v225 offset:4096
	ds_read_b128 v[174:177], v225 offset:5120
	s_waitcnt lgkmcnt(5)
	v_mfma_f32_16x16x32_bf16 v[96:99], v[178:181], v[32:35], v[96:99]
	v_mfma_f32_16x16x32_bf16 v[108:111], v[212:215], v[32:35], v[108:111]
	v_mfma_f32_16x16x32_bf16 v[104:107], v[216:219], v[32:35], v[104:107]
	v_mfma_f32_16x16x32_bf16 v[100:103], v[220:223], v[32:35], v[100:103]
	s_waitcnt lgkmcnt(4)
	v_mfma_f32_16x16x32_bf16 v[92:95], v[178:181], v[36:39], v[92:95]
	v_mfma_f32_16x16x32_bf16 v[88:91], v[212:215], v[36:39], v[88:91]
	v_mfma_f32_16x16x32_bf16 v[84:87], v[216:219], v[36:39], v[84:87]
	v_mfma_f32_16x16x32_bf16 v[80:83], v[220:223], v[36:39], v[80:83]
	s_waitcnt lgkmcnt(3)
	v_mfma_f32_16x16x32_bf16 v[76:79], v[178:181], v[40:43], v[76:79]
	v_mfma_f32_16x16x32_bf16 v[72:75], v[212:215], v[40:43], v[72:75]
	v_mfma_f32_16x16x32_bf16 v[52:55], v[216:219], v[40:43], v[52:55]
	v_mfma_f32_16x16x32_bf16 v[48:51], v[220:223], v[40:43], v[48:51]
	s_waitcnt lgkmcnt(2)
	v_mfma_f32_16x16x32_bf16 v[68:71], v[178:181], v[44:47], v[68:71]
	v_mfma_f32_16x16x32_bf16 v[64:67], v[212:215], v[44:47], v[64:67]
	v_mfma_f32_16x16x32_bf16 v[60:63], v[216:219], v[44:47], v[60:63]
	v_mfma_f32_16x16x32_bf16 v[56:59], v[220:223], v[44:47], v[56:59]
	s_waitcnt lgkmcnt(1)
	v_mfma_f32_16x16x32_bf16 v[28:31], v[178:181], v[134:137], v[28:31]
	v_mfma_f32_16x16x32_bf16 v[24:27], v[212:215], v[134:137], v[24:27]
	v_mfma_f32_16x16x32_bf16 v[20:23], v[216:219], v[134:137], v[20:23]
	v_mfma_f32_16x16x32_bf16 v[16:19], v[220:223], v[134:137], v[16:19]
	s_waitcnt lgkmcnt(0)
	v_mfma_f32_16x16x32_bf16 v[12:15], v[178:181], v[174:177], v[12:15]
	v_mfma_f32_16x16x32_bf16 v[8:11], v[212:215], v[174:177], v[8:11]
	v_mfma_f32_16x16x32_bf16 v[4:7], v[216:219], v[174:177], v[4:7]
	v_mfma_f32_16x16x32_bf16 v[0:3], v[220:223], v[174:177], v[0:3]
	s_mov_b32 s11, 2
	s_mov_b32 s15, 0xf000
	s_branch .LBB0_23

.LBB0_59:
	s_waitcnt vmcnt(0) lgkmcnt(0)
	v_lshrrev_b32_e32 v236, 6, v167
	v_lshlrev_b32_e32 v220, 4, v186
	v_lshlrev_b32_e32 v221, 3, v186
	v_readfirstlane_b32 s2, v236
	v_xor_b32_e32 v222, 32, v186
	v_lshlrev_b32_e32 v222, 2, v222
	v_xor_b32_e32 v223, 16, v186
	v_lshlrev_b32_e32 v223, 2, v223
	v_xor_b32_e32 v224, 8, v186
	v_lshlrev_b32_e32 v224, 2, v224
	v_xor_b32_e32 v225, 4, v186
	v_lshlrev_b32_e32 v225, 2, v225
	v_xor_b32_e32 v234, 2, v186
	v_lshlrev_b32_e32 v234, 2, v234
	v_xor_b32_e32 v235, 1, v186
	v_lshlrev_b32_e32 v235, 2, v235
	v_readlane_b32 s0, v249, 0
	s_lshl_b32 s0, s0, 2
	s_add_i32 s0, s0, s2
	v_readlane_b32 s4, v249, 7
	v_readlane_b32 s5, v249, 8
	s_load_dword s1, s[4:5], 0x0
	v_readlane_b32 s20, v249, 17
	v_readlane_b32 s21, v249, 18
	s_lshl_b32 s2, s38, 12
	s_add_u32 s20, s20, s2
	s_addc_u32 s21, s21, 0
	global_load_dwordx4 v[144:147], v220, s[20:21]
	global_load_dwordx4 v[148:151], v220, s[20:21] offset:1024
	global_load_dwordx4 v[212:215], v220, s[20:21] offset:2048
	global_load_dwordx4 v[216:219], v220, s[20:21] offset:3072
	v_readlane_b32 s22, v248, 37
	v_readlane_b32 s23, v248, 38
	s_mul_i32 s2, s38, 0x12000
	s_add_i32 s2, s2, 0x3000
	s_add_u32 s22, s22, s2
	s_addc_u32 s23, s23, 0
	v_readlane_b32 s24, v249, 3
	v_readlane_b32 s25, v249, 4
	s_waitcnt lgkmcnt(0)
	s_lshl_b32 s1, s1, 2
.Lnmb_pass:
	s_mul_i32 s14, s1, 0
	s_add_i32 s14, s14, s0
	s_min_u32 s14, s14, 0x17ff
	s_add_i32 s15, s14, 0xfffff000
	s_lshr_b32 s15, s15, 10
	s_add_i32 s15, s15, 1
	s_cmp_lt_u32 s14, 0x1000
	s_cselect_b32 s15, 0, s15
	s_mul_i32 s15, s15, 0x6000
	s_add_u32 s6, s22, s15
	s_addc_u32 s7, s23, 0
	s_add_u32 s8, s6, 0x1000
	s_addc_u32 s9, s7, 0
	s_lshl_b32 s15, s14, 12
	v_readlane_b32 s4, v248, 33
	v_readlane_b32 s5, v248, 34
	s_add_u32 s4, s4, s15
	s_addc_u32 s5, s5, 0
	global_load_dwordx4 v[0:3], v220, s[4:5]
	global_load_dwordx4 v[4:7], v220, s[4:5] offset:1024
	global_load_dwordx4 v[8:11], v220, s[4:5] offset:2048
	global_load_dwordx4 v[12:15], v220, s[4:5] offset:3072
	global_load_dwordx4 v[48:51], v220, s[6:7]
	global_load_dwordx4 v[52:55], v220, s[6:7] offset:1024
	global_load_dwordx4 v[56:59], v220, s[6:7] offset:2048
	global_load_dwordx4 v[60:63], v220, s[6:7] offset:3072
	global_load_dwordx4 v[96:99], v220, s[8:9]
	global_load_dwordx4 v[100:103], v220, s[8:9] offset:1024
	global_load_dwordx4 v[104:107], v220, s[8:9] offset:2048
	global_load_dwordx4 v[108:111], v220, s[8:9] offset:3072
	s_mul_i32 s14, s1, 1
	s_add_i32 s14, s14, s0
	s_min_u32 s14, s14, 0x17ff
	s_add_i32 s15, s14, 0xfffff000
	s_lshr_b32 s15, s15, 10
	s_add_i32 s15, s15, 1
	s_cmp_lt_u32 s14, 0x1000
	s_cselect_b32 s15, 0, s15
	s_mul_i32 s15, s15, 0x6000
	s_add_u32 s6, s22, s15
	s_addc_u32 s7, s23, 0
	s_add_u32 s8, s6, 0x1000
	s_addc_u32 s9, s7, 0
	s_lshl_b32 s15, s14, 12
	v_readlane_b32 s4, v248, 33
	v_readlane_b32 s5, v248, 34
	s_add_u32 s4, s4, s15
	s_addc_u32 s5, s5, 0
	global_load_dwordx4 v[16:19], v220, s[4:5]
	global_load_dwordx4 v[20:23], v220, s[4:5] offset:1024
	global_load_dwordx4 v[24:27], v220, s[4:5] offset:2048
	global_load_dwordx4 v[28:31], v220, s[4:5] offset:3072
	global_load_dwordx4 v[64:67], v220, s[6:7]
	global_load_dwordx4 v[68:71], v220, s[6:7] offset:1024
	global_load_dwordx4 v[72:75], v220, s[6:7] offset:2048
	global_load_dwordx4 v[76:79], v220, s[6:7] offset:3072
	global_load_dwordx4 v[112:115], v220, s[8:9]
	global_load_dwordx4 v[116:119], v220, s[8:9] offset:1024
	global_load_dwordx4 v[120:123], v220, s[8:9] offset:2048
	global_load_dwordx4 v[124:127], v220, s[8:9] offset:3072
	s_mul_i32 s14, s1, 2
	s_add_i32 s14, s14, s0
	s_min_u32 s14, s14, 0x17ff
	s_add_i32 s15, s14, 0xfffff000
	s_lshr_b32 s15, s15, 10
	s_add_i32 s15, s15, 1
	s_cmp_lt_u32 s14, 0x1000
	s_cselect_b32 s15, 0, s15
	s_mul_i32 s15, s15, 0x6000
	s_add_u32 s6, s22, s15
	s_addc_u32 s7, s23, 0
	s_add_u32 s8, s6, 0x1000
	s_addc_u32 s9, s7, 0
	s_lshl_b32 s15, s14, 12
	v_readlane_b32 s4, v248, 33
	v_readlane_b32 s5, v248, 34
	s_add_u32 s4, s4, s15
	s_addc_u32 s5, s5, 0
	global_load_dwordx4 v[32:35], v220, s[4:5]
	global_load_dwordx4 v[36:39], v220, s[4:5] offset:1024
	global_load_dwordx4 v[40:43], v220, s[4:5] offset:2048
	global_load_dwordx4 v[44:47], v220, s[4:5] offset:3072
	global_load_dwordx4 v[80:83], v220, s[6:7]
	global_load_dwordx4 v[84:87], v220, s[6:7] offset:1024
	global_load_dwordx4 v[88:91], v220, s[6:7] offset:2048
	global_load_dwordx4 v[92:95], v220, s[6:7] offset:3072
	global_load_dwordx4 v[128:131], v220, s[8:9]
	global_load_dwordx4 v[132:135], v220, s[8:9] offset:1024
	global_load_dwordx4 v[136:139], v220, s[8:9] offset:2048
	global_load_dwordx4 v[140:143], v220, s[8:9] offset:3072
	s_waitcnt vmcnt(32)
	v_mul_f32_e32 v237, v1, v1
	v_fmac_f32_e32 v237, v0, v0
	v_fmac_f32_e32 v237, v2, v2
	v_fmac_f32_e32 v237, v3, v3
	v_mul_f32_e32 v238, v5, v5
	v_fmac_f32_e32 v238, v4, v4
	v_fmac_f32_e32 v238, v6, v6
	v_fmac_f32_e32 v238, v7, v7
	v_mul_f32_e32 v239, v9, v9
	v_fmac_f32_e32 v239, v8, v8
	v_fmac_f32_e32 v239, v10, v10
	v_fmac_f32_e32 v239, v11, v11
	v_mul_f32_e32 v240, v13, v13
	v_fmac_f32_e32 v240, v12, v12
	v_fmac_f32_e32 v240, v14, v14
	v_fmac_f32_e32 v240, v15, v15
	v_add_f32_e32 v237, v237, v238
	v_add_f32_e32 v237, v237, v239
	v_add_f32_e32 v237, v237, v240
	ds_bpermute_b32 v241, v222, v237
	s_waitcnt lgkmcnt(0)
	v_add_f32_e32 v237, v237, v241
	ds_bpermute_b32 v241, v223, v237
	s_waitcnt lgkmcnt(0)
	v_add_f32_e32 v237, v237, v241
	ds_bpermute_b32 v241, v224, v237
	s_waitcnt lgkmcnt(0)
	v_add_f32_e32 v237, v237, v241
	ds_bpermute_b32 v241, v225, v237
	s_waitcnt lgkmcnt(0)
	v_add_f32_e32 v237, v237, v241
	ds_bpermute_b32 v241, v234, v237
	s_waitcnt lgkmcnt(0)
	v_add_f32_e32 v237, v237, v241
	ds_bpermute_b32 v241, v235, v237
	s_waitcnt lgkmcnt(0)
	v_add_f32_e32 v237, v237, v241
	v_fmamk_f32 v237, v237, 0x3a800000, v171
	s_mov_b32 s15, 0x800000
	v_cmp_gt_f32_e32 vcc, s15, v237
	v_mul_f32_e32 v241, 0x4b800000, v237
	s_nop 0
	v_cndmask_b32_e32 v237, v237, v241, vcc
	v_rsq_f32_e32 v237, v237
	s_nop 0
	v_mul_f32_e32 v241, 0x45800000, v237
	v_cndmask_b32_e32 v242, v237, v241, vcc
	s_waitcnt vmcnt(24)
	v_pk_mul_f32 v[0:1], v[0:1], v[242:243] op_sel_hi:[1,0]
	v_pk_mul_f32 v[0:1], v[144:145], v[0:1]
	v_pk_add_f32 v[96:97], v[96:97], 1.0 op_sel_hi:[1,0]
	v_pk_fma_f32 v[0:1], v[96:97], v[0:1], v[48:49]
	v_pk_mul_f32 v[2:3], v[2:3], v[242:243] op_sel_hi:[1,0]
	v_pk_mul_f32 v[2:3], v[146:147], v[2:3]
	v_pk_add_f32 v[98:99], v[98:99], 1.0 op_sel_hi:[1,0]
	v_pk_fma_f32 v[2:3], v[98:99], v[2:3], v[50:51]
	v_cvt_pk_bf16_f32 v0, v0, v1
	v_cvt_pk_bf16_f32 v1, v2, v3
	v_pk_mul_f32 v[4:5], v[4:5], v[242:243] op_sel_hi:[1,0]
	v_pk_mul_f32 v[4:5], v[148:149], v[4:5]
	v_pk_add_f32 v[100:101], v[100:101], 1.0 op_sel_hi:[1,0]
	v_pk_fma_f32 v[4:5], v[100:101], v[4:5], v[52:53]
	v_pk_mul_f32 v[6:7], v[6:7], v[242:243] op_sel_hi:[1,0]
	v_pk_mul_f32 v[6:7], v[150:151], v[6:7]
	v_pk_add_f32 v[102:103], v[102:103], 1.0 op_sel_hi:[1,0]
	v_pk_fma_f32 v[6:7], v[102:103], v[6:7], v[54:55]
	v_cvt_pk_bf16_f32 v4, v4, v5
	v_cvt_pk_bf16_f32 v5, v6, v7
	v_pk_mul_f32 v[8:9], v[8:9], v[242:243] op_sel_hi:[1,0]
	v_pk_mul_f32 v[8:9], v[212:213], v[8:9]
	v_pk_add_f32 v[104:105], v[104:105], 1.0 op_sel_hi:[1,0]
	v_pk_fma_f32 v[8:9], v[104:105], v[8:9], v[56:57]
	v_pk_mul_f32 v[10:11], v[10:11], v[242:243] op_sel_hi:[1,0]
	v_pk_mul_f32 v[10:11], v[214:215], v[10:11]
	v_pk_add_f32 v[106:107], v[106:107], 1.0 op_sel_hi:[1,0]
	v_pk_fma_f32 v[10:11], v[106:107], v[10:11], v[58:59]
	v_cvt_pk_bf16_f32 v8, v8, v9
	v_cvt_pk_bf16_f32 v9, v10, v11
	v_pk_mul_f32 v[12:13], v[12:13], v[242:243] op_sel_hi:[1,0]
	v_pk_mul_f32 v[12:13], v[216:217], v[12:13]
	v_pk_add_f32 v[108:109], v[108:109], 1.0 op_sel_hi:[1,0]
	v_pk_fma_f32 v[12:13], v[108:109], v[12:13], v[60:61]
	v_pk_mul_f32 v[14:15], v[14:15], v[242:243] op_sel_hi:[1,0]
	v_pk_mul_f32 v[14:15], v[218:219], v[14:15]
	v_pk_add_f32 v[110:111], v[110:111], 1.0 op_sel_hi:[1,0]
	v_pk_fma_f32 v[14:15], v[110:111], v[14:15], v[62:63]
	v_cvt_pk_bf16_f32 v12, v12, v13
	v_cvt_pk_bf16_f32 v13, v14, v15
	s_mul_i32 s14, s1, 0
	s_add_i32 s14, s14, s0
	s_cmpk_lt_u32 s14, 0x1800
	s_cbranch_scc0 .Lnmb_done
	s_lshl_b32 s14, s14, 11
	s_add_u32 s10, s24, s14
	s_addc_u32 s11, s25, 0
	global_store_dwordx2 v221, v[0:1], s[10:11]
	global_store_dwordx2 v221, v[4:5], s[10:11] offset:512
	global_store_dwordx2 v221, v[8:9], s[10:11] offset:1024
	global_store_dwordx2 v221, v[12:13], s[10:11] offset:1536
	s_waitcnt vmcnt(24)
	v_mul_f32_e32 v237, v17, v17
	v_fmac_f32_e32 v237, v16, v16
	v_fmac_f32_e32 v237, v18, v18
	v_fmac_f32_e32 v237, v19, v19
	v_mul_f32_e32 v238, v21, v21
	v_fmac_f32_e32 v238, v20, v20
	v_fmac_f32_e32 v238, v22, v22
	v_fmac_f32_e32 v238, v23, v23
	v_mul_f32_e32 v239, v25, v25
	v_fmac_f32_e32 v239, v24, v24
	v_fmac_f32_e32 v239, v26, v26
	v_fmac_f32_e32 v239, v27, v27
	v_mul_f32_e32 v240, v29, v29
	v_fmac_f32_e32 v240, v28, v28
	v_fmac_f32_e32 v240, v30, v30
	v_fmac_f32_e32 v240, v31, v31
	v_add_f32_e32 v237, v237, v238
	v_add_f32_e32 v237, v237, v239
	v_add_f32_e32 v237, v237, v240
	ds_bpermute_b32 v241, v222, v237
	s_waitcnt lgkmcnt(0)
	v_add_f32_e32 v237, v237, v241
	ds_bpermute_b32 v241, v223, v237
	s_waitcnt lgkmcnt(0)
	v_add_f32_e32 v237, v237, v241
	ds_bpermute_b32 v241, v224, v237
	s_waitcnt lgkmcnt(0)
	v_add_f32_e32 v237, v237, v241
	ds_bpermute_b32 v241, v225, v237
	s_waitcnt lgkmcnt(0)
	v_add_f32_e32 v237, v237, v241
	ds_bpermute_b32 v241, v234, v237
	s_waitcnt lgkmcnt(0)
	v_add_f32_e32 v237, v237, v241
	ds_bpermute_b32 v241, v235, v237
	s_waitcnt lgkmcnt(0)
	v_add_f32_e32 v237, v237, v241
	v_fmamk_f32 v237, v237, 0x3a800000, v171
	s_mov_b32 s15, 0x800000
	v_cmp_gt_f32_e32 vcc, s15, v237
	v_mul_f32_e32 v241, 0x4b800000, v237
	s_nop 0
	v_cndmask_b32_e32 v237, v237, v241, vcc
	v_rsq_f32_e32 v237, v237
	s_nop 0
	v_mul_f32_e32 v241, 0x45800000, v237
	v_cndmask_b32_e32 v242, v237, v241, vcc
	s_waitcnt vmcnt(16)
	v_pk_mul_f32 v[16:17], v[16:17], v[242:243] op_sel_hi:[1,0]
	v_pk_mul_f32 v[16:17], v[144:145], v[16:17]
	v_pk_add_f32 v[112:113], v[112:113], 1.0 op_sel_hi:[1,0]
	v_pk_fma_f32 v[16:17], v[112:113], v[16:17], v[64:65]
	v_pk_mul_f32 v[18:19], v[18:19], v[242:243] op_sel_hi:[1,0]
	v_pk_mul_f32 v[18:19], v[146:147], v[18:19]
	v_pk_add_f32 v[114:115], v[114:115], 1.0 op_sel_hi:[1,0]
	v_pk_fma_f32 v[18:19], v[114:115], v[18:19], v[66:67]
	v_cvt_pk_bf16_f32 v16, v16, v17
	v_cvt_pk_bf16_f32 v17, v18, v19
	v_pk_mul_f32 v[20:21], v[20:21], v[242:243] op_sel_hi:[1,0]
	v_pk_mul_f32 v[20:21], v[148:149], v[20:21]
	v_pk_add_f32 v[116:117], v[116:117], 1.0 op_sel_hi:[1,0]
	v_pk_fma_f32 v[20:21], v[116:117], v[20:21], v[68:69]
	v_pk_mul_f32 v[22:23], v[22:23], v[242:243] op_sel_hi:[1,0]
	v_pk_mul_f32 v[22:23], v[150:151], v[22:23]
	v_pk_add_f32 v[118:119], v[118:119], 1.0 op_sel_hi:[1,0]
	v_pk_fma_f32 v[22:23], v[118:119], v[22:23], v[70:71]
	v_cvt_pk_bf16_f32 v20, v20, v21
	v_cvt_pk_bf16_f32 v21, v22, v23
	v_pk_mul_f32 v[24:25], v[24:25], v[242:243] op_sel_hi:[1,0]
	v_pk_mul_f32 v[24:25], v[212:213], v[24:25]
	v_pk_add_f32 v[120:121], v[120:121], 1.0 op_sel_hi:[1,0]
	v_pk_fma_f32 v[24:25], v[120:121], v[24:25], v[72:73]
	v_pk_mul_f32 v[26:27], v[26:27], v[242:243] op_sel_hi:[1,0]
	v_pk_mul_f32 v[26:27], v[214:215], v[26:27]
	v_pk_add_f32 v[122:123], v[122:123], 1.0 op_sel_hi:[1,0]
	v_pk_fma_f32 v[26:27], v[122:123], v[26:27], v[74:75]
	v_cvt_pk_bf16_f32 v24, v24, v25
	v_cvt_pk_bf16_f32 v25, v26, v27
	v_pk_mul_f32 v[28:29], v[28:29], v[242:243] op_sel_hi:[1,0]
	v_pk_mul_f32 v[28:29], v[216:217], v[28:29]
	v_pk_add_f32 v[124:125], v[124:125], 1.0 op_sel_hi:[1,0]
	v_pk_fma_f32 v[28:29], v[124:125], v[28:29], v[76:77]
	v_pk_mul_f32 v[30:31], v[30:31], v[242:243] op_sel_hi:[1,0]
	v_pk_mul_f32 v[30:31], v[218:219], v[30:31]
	v_pk_add_f32 v[126:127], v[126:127], 1.0 op_sel_hi:[1,0]
	v_pk_fma_f32 v[30:31], v[126:127], v[30:31], v[78:79]
	v_cvt_pk_bf16_f32 v28, v28, v29
	v_cvt_pk_bf16_f32 v29, v30, v31
	s_mul_i32 s14, s1, 1
	s_add_i32 s14, s14, s0
	s_cmpk_lt_u32 s14, 0x1800
	s_cbranch_scc0 .Lnmb_done
	s_lshl_b32 s14, s14, 11
	s_add_u32 s10, s24, s14
	s_addc_u32 s11, s25, 0
	global_store_dwordx2 v221, v[16:17], s[10:11]
	global_store_dwordx2 v221, v[20:21], s[10:11] offset:512
	global_store_dwordx2 v221, v[24:25], s[10:11] offset:1024
	global_store_dwordx2 v221, v[28:29], s[10:11] offset:1536
	s_waitcnt vmcnt(16)
	v_mul_f32_e32 v237, v33, v33
	v_fmac_f32_e32 v237, v32, v32
	v_fmac_f32_e32 v237, v34, v34
	v_fmac_f32_e32 v237, v35, v35
	v_mul_f32_e32 v238, v37, v37
	v_fmac_f32_e32 v238, v36, v36
	v_fmac_f32_e32 v238, v38, v38
	v_fmac_f32_e32 v238, v39, v39
	v_mul_f32_e32 v239, v41, v41
	v_fmac_f32_e32 v239, v40, v40
	v_fmac_f32_e32 v239, v42, v42
	v_fmac_f32_e32 v239, v43, v43
	v_mul_f32_e32 v240, v45, v45
	v_fmac_f32_e32 v240, v44, v44
	v_fmac_f32_e32 v240, v46, v46
	v_fmac_f32_e32 v240, v47, v47
	v_add_f32_e32 v237, v237, v238
	v_add_f32_e32 v237, v237, v239
	v_add_f32_e32 v237, v237, v240
	ds_bpermute_b32 v241, v222, v237
	s_waitcnt lgkmcnt(0)
	v_add_f32_e32 v237, v237, v241
	ds_bpermute_b32 v241, v223, v237
	s_waitcnt lgkmcnt(0)
	v_add_f32_e32 v237, v237, v241
	ds_bpermute_b32 v241, v224, v237
	s_waitcnt lgkmcnt(0)
	v_add_f32_e32 v237, v237, v241
	ds_bpermute_b32 v241, v225, v237
	s_waitcnt lgkmcnt(0)
	v_add_f32_e32 v237, v237, v241
	ds_bpermute_b32 v241, v234, v237
	s_waitcnt lgkmcnt(0)
	v_add_f32_e32 v237, v237, v241
	ds_bpermute_b32 v241, v235, v237
	s_waitcnt lgkmcnt(0)
	v_add_f32_e32 v237, v237, v241
	v_fmamk_f32 v237, v237, 0x3a800000, v171
	s_mov_b32 s15, 0x800000
	v_cmp_gt_f32_e32 vcc, s15, v237
	v_mul_f32_e32 v241, 0x4b800000, v237
	s_nop 0
	v_cndmask_b32_e32 v237, v237, v241, vcc
	v_rsq_f32_e32 v237, v237
	s_nop 0
	v_mul_f32_e32 v241, 0x45800000, v237
	v_cndmask_b32_e32 v242, v237, v241, vcc
	s_waitcnt vmcnt(8)
	v_pk_mul_f32 v[32:33], v[32:33], v[242:243] op_sel_hi:[1,0]
	v_pk_mul_f32 v[32:33], v[144:145], v[32:33]
	v_pk_add_f32 v[128:129], v[128:129], 1.0 op_sel_hi:[1,0]
	v_pk_fma_f32 v[32:33], v[128:129], v[32:33], v[80:81]
	v_pk_mul_f32 v[34:35], v[34:35], v[242:243] op_sel_hi:[1,0]
	v_pk_mul_f32 v[34:35], v[146:147], v[34:35]
	v_pk_add_f32 v[130:131], v[130:131], 1.0 op_sel_hi:[1,0]
	v_pk_fma_f32 v[34:35], v[130:131], v[34:35], v[82:83]
	v_cvt_pk_bf16_f32 v32, v32, v33
	v_cvt_pk_bf16_f32 v33, v34, v35
	v_pk_mul_f32 v[36:37], v[36:37], v[242:243] op_sel_hi:[1,0]
	v_pk_mul_f32 v[36:37], v[148:149], v[36:37]
	v_pk_add_f32 v[132:133], v[132:133], 1.0 op_sel_hi:[1,0]
	v_pk_fma_f32 v[36:37], v[132:133], v[36:37], v[84:85]
	v_pk_mul_f32 v[38:39], v[38:39], v[242:243] op_sel_hi:[1,0]
	v_pk_mul_f32 v[38:39], v[150:151], v[38:39]
	v_pk_add_f32 v[134:135], v[134:135], 1.0 op_sel_hi:[1,0]
	v_pk_fma_f32 v[38:39], v[134:135], v[38:39], v[86:87]
	v_cvt_pk_bf16_f32 v36, v36, v37
	v_cvt_pk_bf16_f32 v37, v38, v39
	v_pk_mul_f32 v[40:41], v[40:41], v[242:243] op_sel_hi:[1,0]
	v_pk_mul_f32 v[40:41], v[212:213], v[40:41]
	v_pk_add_f32 v[136:137], v[136:137], 1.0 op_sel_hi:[1,0]
	v_pk_fma_f32 v[40:41], v[136:137], v[40:41], v[88:89]
	v_pk_mul_f32 v[42:43], v[42:43], v[242:243] op_sel_hi:[1,0]
	v_pk_mul_f32 v[42:43], v[214:215], v[42:43]
	v_pk_add_f32 v[138:139], v[138:139], 1.0 op_sel_hi:[1,0]
	v_pk_fma_f32 v[42:43], v[138:139], v[42:43], v[90:91]
	v_cvt_pk_bf16_f32 v40, v40, v41
	v_cvt_pk_bf16_f32 v41, v42, v43
	v_pk_mul_f32 v[44:45], v[44:45], v[242:243] op_sel_hi:[1,0]
	v_pk_mul_f32 v[44:45], v[216:217], v[44:45]
	v_pk_add_f32 v[140:141], v[140:141], 1.0 op_sel_hi:[1,0]
	v_pk_fma_f32 v[44:45], v[140:141], v[44:45], v[92:93]
	v_pk_mul_f32 v[46:47], v[46:47], v[242:243] op_sel_hi:[1,0]
	v_pk_mul_f32 v[46:47], v[218:219], v[46:47]
	v_pk_add_f32 v[142:143], v[142:143], 1.0 op_sel_hi:[1,0]
	v_pk_fma_f32 v[46:47], v[142:143], v[46:47], v[94:95]
	v_cvt_pk_bf16_f32 v44, v44, v45
	v_cvt_pk_bf16_f32 v45, v46, v47
	s_mul_i32 s14, s1, 2
	s_add_i32 s14, s14, s0
	s_cmpk_lt_u32 s14, 0x1800
	s_cbranch_scc0 .Lnmb_done
	s_lshl_b32 s14, s14, 11
	s_add_u32 s10, s24, s14
	s_addc_u32 s11, s25, 0
	global_store_dwordx2 v221, v[32:33], s[10:11]
	global_store_dwordx2 v221, v[36:37], s[10:11] offset:512
	global_store_dwordx2 v221, v[40:41], s[10:11] offset:1024
	global_store_dwordx2 v221, v[44:45], s[10:11] offset:1536
	s_mul_i32 s14, s1, 3
	s_add_i32 s0, s0, s14
	s_cmpk_lt_u32 s0, 0x1800
	s_cbranch_scc1 .Lnmb_pass
.Lnmb_done:
.LBB0_63:
	s_mov_b64 s[0:1], 0

.LBB0_361:
	s_cmp_lg_u64 s[2:3], 0
	s_cselect_b32 s10, 1, 0
	s_mul_i32 s2, s30, 0xc0
	s_lshl_b32 s11, s29, 7
	s_mov_b32 s8, s11
	v_readlane_b32 s24, v249, 3
	v_readlane_b32 s25, v249, 4
	s_lshl_b32 s0, s2, 11
	s_add_u32 s24, s24, s0
	s_addc_u32 s25, s25, 0
	s_lshl_b32 s0, s8, 11
	s_add_u32 s36, s6, s0
	s_addc_u32 s37, s7, 0
	v_lshrrev_b32_e32 v246, 6, v167
	v_and_b32_e32 v234, 15, v167
	v_bfe_u32 v235, v167, 4, 2
	v_readfirstlane_b32 s14, v246
	v_lshrrev_b32_e32 v239, 1, v234
	v_xor_b32_e32 v239, v239, v235
	v_lshlrev_b32_e32 v239, 4, v239
	v_lshl_add_u32 v239, v234, 7, v239
	v_lshrrev_b32_e32 v241, 1, v246
	v_mul_u32_u24_e32 v241, 0x3000, v241
	v_add_u32_e32 v238, v241, v239
	v_and_b32_e32 v241, 1, v246
	v_lshlrev_b32_e32 v241, 13, v241
	v_add_u32_e32 v240, v241, v239
	v_add_u32_e32 v240, 0x6000, v240
	v_xor_b32_e32 v239, 64, v238
	v_xor_b32_e32 v241, 64, v240
	v_lshrrev_b32_e32 v234, 3, v167
	v_bfe_u32 v235, v167, 4, 3
	v_and_b32_e32 v242, 7, v167
	v_xor_b32_e32 v242, v242, v235
	v_lshlrev_b32_e32 v242, 4, v242
	v_lshl_add_u32 v242, v234, 11, v242
	v_lshrrev_b32_e32 v234, 2, v167
	v_lshrrev_b32_e32 v235, 4, v167
	v_sub_u32_e32 v235, 0, v235
	v_xor_b32_e32 v235, v235, v167
	v_and_b32_e32 v235, 3, v235
	v_lshlrev_b32_e32 v243, 4, v235
	v_lshl_add_u32 v243, v234, 11, v243
	v_lshlrev_b32_e32 v244, 1, v159
	v_add_u32_e32 v244, 0xa000, v244
	v_lshlrev_b32_e32 v245, 1, v212
	v_add_u32_e32 v245, 0xa000, v245
	s_lshl_b32 s14, s14, 10
	s_mov_b64 s[16:17], s[24:25]
	s_mov_b64 s[22:23], s[36:37]
	s_cmp_lg_u32 s10, 0
	s_cbranch_scc1 .Lk64gin_pre
	s_barrier
	s_add_u32 m0, s14, 0x0
	s_nop 0
	global_load_lds_dwordx4 v242, s[16:17]
	s_add_u32 m0, s14, 0x1000
	s_add_u32 s0, s16, 0x10000
	s_addc_u32 s1, s17, 0
	global_load_lds_dwordx4 v242, s[0:1]
	s_add_u32 m0, s14, 0x2000
	s_add_u32 s0, s16, 0x20000
	s_addc_u32 s1, s17, 0
	global_load_lds_dwordx4 v242, s[0:1]
	s_add_u32 m0, s14, 0x3000
	s_add_u32 s0, s16, 0x30000
	s_addc_u32 s1, s17, 0
	global_load_lds_dwordx4 v242, s[0:1]
	s_add_u32 m0, s14, 0x4000
	s_add_u32 s0, s16, 0x40000
	s_addc_u32 s1, s17, 0
	global_load_lds_dwordx4 v242, s[0:1]
	s_add_u32 m0, s14, 0x5000
	s_add_u32 s0, s16, 0x50000
	s_addc_u32 s1, s17, 0
	global_load_lds_dwordx4 v242, s[0:1]
	s_add_u32 m0, s14, 0x6000
	s_nop 0
	global_load_lds_dwordx4 v242, s[22:23]
	s_add_u32 m0, s14, 0x7000
	s_add_u32 s0, s22, 0x10000
	s_addc_u32 s1, s23, 0
	global_load_lds_dwordx4 v242, s[0:1]
	s_add_u32 m0, s14, 0x8000
	s_add_u32 s0, s22, 0x20000
	s_addc_u32 s1, s23, 0
	global_load_lds_dwordx4 v242, s[0:1]
	s_add_u32 m0, s14, 0x9000
	s_add_u32 s0, s22, 0x30000
	s_addc_u32 s1, s23, 0
	global_load_lds_dwordx4 v242, s[0:1]
.Lk64gin_pre:
	s_add_u32 s16, s16, 0x80
	s_addc_u32 s17, s17, 0
	s_add_u32 s22, s22, 0x80
	s_addc_u32 s23, s23, 0
	v_mov_b32_e32 v108, 0
	v_mov_b32_e32 v109, 0
	v_mov_b32_e32 v110, 0
	v_mov_b32_e32 v111, 0
	v_mov_b32_e32 v96, 0
	v_mov_b32_e32 v97, 0
	v_mov_b32_e32 v98, 0
	v_mov_b32_e32 v99, 0
	v_mov_b32_e32 v104, 0
	v_mov_b32_e32 v105, 0
	v_mov_b32_e32 v106, 0
	v_mov_b32_e32 v107, 0
	v_mov_b32_e32 v116, 0
	v_mov_b32_e32 v117, 0
	v_mov_b32_e32 v118, 0
	v_mov_b32_e32 v119, 0
	v_mov_b32_e32 v76, 0
	v_mov_b32_e32 v77, 0
	v_mov_b32_e32 v78, 0
	v_mov_b32_e32 v79, 0
	v_mov_b32_e32 v72, 0
	v_mov_b32_e32 v73, 0
	v_mov_b32_e32 v74, 0
	v_mov_b32_e32 v75, 0
	v_mov_b32_e32 v68, 0
	v_mov_b32_e32 v69, 0
	v_mov_b32_e32 v70, 0
	v_mov_b32_e32 v71, 0
	v_mov_b32_e32 v64, 0
	v_mov_b32_e32 v65, 0
	v_mov_b32_e32 v66, 0
	v_mov_b32_e32 v67, 0
	v_mov_b32_e32 v120, 0
	v_mov_b32_e32 v121, 0
	v_mov_b32_e32 v122, 0
	v_mov_b32_e32 v123, 0
	v_mov_b32_e32 v124, 0
	v_mov_b32_e32 v125, 0
	v_mov_b32_e32 v126, 0
	v_mov_b32_e32 v127, 0
	v_mov_b32_e32 v128, 0
	v_mov_b32_e32 v129, 0
	v_mov_b32_e32 v130, 0
	v_mov_b32_e32 v131, 0
	v_mov_b32_e32 v132, 0
	v_mov_b32_e32 v133, 0
	v_mov_b32_e32 v134, 0
	v_mov_b32_e32 v135, 0
	v_mov_b32_e32 v44, 0
	v_mov_b32_e32 v45, 0
	v_mov_b32_e32 v46, 0
	v_mov_b32_e32 v47, 0
	v_mov_b32_e32 v40, 0
	v_mov_b32_e32 v41, 0
	v_mov_b32_e32 v42, 0
	v_mov_b32_e32 v43, 0
	v_mov_b32_e32 v36, 0
	v_mov_b32_e32 v37, 0
	v_mov_b32_e32 v38, 0
	v_mov_b32_e32 v39, 0
	v_mov_b32_e32 v32, 0
	v_mov_b32_e32 v33, 0
	v_mov_b32_e32 v34, 0
	v_mov_b32_e32 v35, 0
	v_mov_b32_e32 v136, 0
	v_mov_b32_e32 v137, 0
	v_mov_b32_e32 v138, 0
	v_mov_b32_e32 v139, 0
	v_mov_b32_e32 v140, 0
	v_mov_b32_e32 v141, 0
	v_mov_b32_e32 v142, 0
	v_mov_b32_e32 v143, 0
	v_mov_b32_e32 v144, 0
	v_mov_b32_e32 v145, 0
	v_mov_b32_e32 v146, 0
	v_mov_b32_e32 v147, 0
	v_mov_b32_e32 v148, 0
	v_mov_b32_e32 v149, 0
	v_mov_b32_e32 v150, 0
	v_mov_b32_e32 v151, 0
	v_mov_b32_e32 v28, 0
	v_mov_b32_e32 v29, 0
	v_mov_b32_e32 v30, 0
	v_mov_b32_e32 v31, 0
	v_mov_b32_e32 v112, 0
	v_mov_b32_e32 v113, 0
	v_mov_b32_e32 v114, 0
	v_mov_b32_e32 v115, 0
	v_mov_b32_e32 v24, 0
	v_mov_b32_e32 v25, 0
	v_mov_b32_e32 v26, 0
	v_mov_b32_e32 v27, 0
	v_mov_b32_e32 v16, 0
	v_mov_b32_e32 v17, 0
	v_mov_b32_e32 v18, 0
	v_mov_b32_e32 v19, 0
	s_mov_b32 s15, 7
.Lk64gin_loop:
	s_waitcnt vmcnt(0)
	s_barrier
	s_add_u32 m0, s14, 0xa000
	s_nop 0
	global_load_lds_dwordx4 v242, s[16:17]
	s_add_u32 m0, s14, 0xb000
	s_add_u32 s0, s16, 0x10000
	s_addc_u32 s1, s17, 0
	global_load_lds_dwordx4 v242, s[0:1]
	s_add_u32 m0, s14, 0xc000
	s_add_u32 s0, s16, 0x20000
	s_addc_u32 s1, s17, 0
	global_load_lds_dwordx4 v242, s[0:1]
	s_add_u32 m0, s14, 0xd000
	s_add_u32 s0, s16, 0x30000
	s_addc_u32 s1, s17, 0
	global_load_lds_dwordx4 v242, s[0:1]
	s_add_u32 m0, s14, 0xe000
	s_add_u32 s0, s16, 0x40000
	s_addc_u32 s1, s17, 0
	global_load_lds_dwordx4 v242, s[0:1]
	s_add_u32 m0, s14, 0xf000
	s_add_u32 s0, s16, 0x50000
	s_addc_u32 s1, s17, 0
	global_load_lds_dwordx4 v242, s[0:1]
	s_add_u32 m0, s14, 0x10000
	s_nop 0
	global_load_lds_dwordx4 v242, s[22:23]
	s_add_u32 m0, s14, 0x11000
	s_add_u32 s0, s22, 0x10000
	s_addc_u32 s1, s23, 0
	global_load_lds_dwordx4 v242, s[0:1]
	s_add_u32 m0, s14, 0x12000
	s_add_u32 s0, s22, 0x20000
	s_addc_u32 s1, s23, 0
	global_load_lds_dwordx4 v242, s[0:1]
	s_add_u32 m0, s14, 0x13000
	s_add_u32 s0, s22, 0x30000
	s_addc_u32 s1, s23, 0
	global_load_lds_dwordx4 v242, s[0:1]
	s_add_u32 s16, s16, 0x80
	s_addc_u32 s17, s17, 0
	s_add_u32 s22, s22, 0x80
	s_addc_u32 s23, s23, 0
	ds_read_b128 v[88:91], v240 offset:0
	ds_read_b128 v[92:95], v240 offset:2048
	ds_read_b128 v[100:103], v240 offset:4096
	ds_read_b128 v[180:183], v240 offset:6144
	ds_read_b128 v[48:51], v238 offset:0
	ds_read_b128 v[52:55], v238 offset:2048
	ds_read_b128 v[56:59], v238 offset:4096
	ds_read_b128 v[60:63], v238 offset:6144
	ds_read_b128 v[80:83], v238 offset:8192
	ds_read_b128 v[84:87], v238 offset:10240
	s_waitcnt lgkmcnt(5)
	v_mfma_f32_16x16x32_bf16 v[108:111], v[88:91], v[48:51], v[108:111]
	v_mfma_f32_16x16x32_bf16 v[96:99], v[92:95], v[48:51], v[96:99]
	v_mfma_f32_16x16x32_bf16 v[104:107], v[100:103], v[48:51], v[104:107]
	v_mfma_f32_16x16x32_bf16 v[116:119], v[180:183], v[48:51], v[116:119]
	s_waitcnt lgkmcnt(4)
	v_mfma_f32_16x16x32_bf16 v[76:79], v[88:91], v[52:55], v[76:79]
	v_mfma_f32_16x16x32_bf16 v[72:75], v[92:95], v[52:55], v[72:75]
	v_mfma_f32_16x16x32_bf16 v[68:71], v[100:103], v[52:55], v[68:71]
	v_mfma_f32_16x16x32_bf16 v[64:67], v[180:183], v[52:55], v[64:67]
	s_waitcnt lgkmcnt(3)
	v_mfma_f32_16x16x32_bf16 v[120:123], v[88:91], v[56:59], v[120:123]
	v_mfma_f32_16x16x32_bf16 v[124:127], v[92:95], v[56:59], v[124:127]
	v_mfma_f32_16x16x32_bf16 v[128:131], v[100:103], v[56:59], v[128:131]
	v_mfma_f32_16x16x32_bf16 v[132:135], v[180:183], v[56:59], v[132:135]
	s_waitcnt lgkmcnt(2)
	v_mfma_f32_16x16x32_bf16 v[44:47], v[88:91], v[60:63], v[44:47]
	v_mfma_f32_16x16x32_bf16 v[40:43], v[92:95], v[60:63], v[40:43]
	v_mfma_f32_16x16x32_bf16 v[36:39], v[100:103], v[60:63], v[36:39]
	v_mfma_f32_16x16x32_bf16 v[32:35], v[180:183], v[60:63], v[32:35]
	s_waitcnt lgkmcnt(1)
	v_mfma_f32_16x16x32_bf16 v[136:139], v[88:91], v[80:83], v[136:139]
	v_mfma_f32_16x16x32_bf16 v[140:143], v[92:95], v[80:83], v[140:143]
	v_mfma_f32_16x16x32_bf16 v[144:147], v[100:103], v[80:83], v[144:147]
	v_mfma_f32_16x16x32_bf16 v[148:151], v[180:183], v[80:83], v[148:151]
	s_waitcnt lgkmcnt(0)
	v_mfma_f32_16x16x32_bf16 v[28:31], v[88:91], v[84:87], v[28:31]
	v_mfma_f32_16x16x32_bf16 v[112:115], v[92:95], v[84:87], v[112:115]
	v_mfma_f32_16x16x32_bf16 v[24:27], v[100:103], v[84:87], v[24:27]
	v_mfma_f32_16x16x32_bf16 v[16:19], v[180:183], v[84:87], v[16:19]
	ds_read_b128 v[88:91], v241 offset:0
	ds_read_b128 v[92:95], v241 offset:2048
	ds_read_b128 v[100:103], v241 offset:4096
	ds_read_b128 v[180:183], v241 offset:6144
	ds_read_b128 v[48:51], v239 offset:0
	ds_read_b128 v[52:55], v239 offset:2048
	ds_read_b128 v[56:59], v239 offset:4096
	ds_read_b128 v[60:63], v239 offset:6144
	ds_read_b128 v[80:83], v239 offset:8192
	ds_read_b128 v[84:87], v239 offset:10240
	s_waitcnt lgkmcnt(5)
	v_mfma_f32_16x16x32_bf16 v[108:111], v[88:91], v[48:51], v[108:111]
	v_mfma_f32_16x16x32_bf16 v[96:99], v[92:95], v[48:51], v[96:99]
	v_mfma_f32_16x16x32_bf16 v[104:107], v[100:103], v[48:51], v[104:107]
	v_mfma_f32_16x16x32_bf16 v[116:119], v[180:183], v[48:51], v[116:119]
	s_waitcnt lgkmcnt(4)
	v_mfma_f32_16x16x32_bf16 v[76:79], v[88:91], v[52:55], v[76:79]
	v_mfma_f32_16x16x32_bf16 v[72:75], v[92:95], v[52:55], v[72:75]
	v_mfma_f32_16x16x32_bf16 v[68:71], v[100:103], v[52:55], v[68:71]
	v_mfma_f32_16x16x32_bf16 v[64:67], v[180:183], v[52:55], v[64:67]
	s_waitcnt lgkmcnt(3)
	v_mfma_f32_16x16x32_bf16 v[120:123], v[88:91], v[56:59], v[120:123]
	v_mfma_f32_16x16x32_bf16 v[124:127], v[92:95], v[56:59], v[124:127]
	v_mfma_f32_16x16x32_bf16 v[128:131], v[100:103], v[56:59], v[128:131]
	v_mfma_f32_16x16x32_bf16 v[132:135], v[180:183], v[56:59], v[132:135]
	s_waitcnt lgkmcnt(2)
	v_mfma_f32_16x16x32_bf16 v[44:47], v[88:91], v[60:63], v[44:47]
	v_mfma_f32_16x16x32_bf16 v[40:43], v[92:95], v[60:63], v[40:43]
	v_mfma_f32_16x16x32_bf16 v[36:39], v[100:103], v[60:63], v[36:39]
	v_mfma_f32_16x16x32_bf16 v[32:35], v[180:183], v[60:63], v[32:35]
	s_waitcnt lgkmcnt(1)
	v_mfma_f32_16x16x32_bf16 v[136:139], v[88:91], v[80:83], v[136:139]
	v_mfma_f32_16x16x32_bf16 v[140:143], v[92:95], v[80:83], v[140:143]
	v_mfma_f32_16x16x32_bf16 v[144:147], v[100:103], v[80:83], v[144:147]
	v_mfma_f32_16x16x32_bf16 v[148:151], v[180:183], v[80:83], v[148:151]
	s_waitcnt lgkmcnt(0)
	v_mfma_f32_16x16x32_bf16 v[28:31], v[88:91], v[84:87], v[28:31]
	v_mfma_f32_16x16x32_bf16 v[112:115], v[92:95], v[84:87], v[112:115]
	v_mfma_f32_16x16x32_bf16 v[24:27], v[100:103], v[84:87], v[24:27]
	v_mfma_f32_16x16x32_bf16 v[16:19], v[180:183], v[84:87], v[16:19]
	s_waitcnt vmcnt(0)
	s_barrier
	s_add_u32 m0, s14, 0x0
	s_nop 0
	global_load_lds_dwordx4 v242, s[16:17]
	s_add_u32 m0, s14, 0x1000
	s_add_u32 s0, s16, 0x10000
	s_addc_u32 s1, s17, 0
	global_load_lds_dwordx4 v242, s[0:1]
	s_add_u32 m0, s14, 0x2000
	s_add_u32 s0, s16, 0x20000
	s_addc_u32 s1, s17, 0
	global_load_lds_dwordx4 v242, s[0:1]
	s_add_u32 m0, s14, 0x3000
	s_add_u32 s0, s16, 0x30000
	s_addc_u32 s1, s17, 0
	global_load_lds_dwordx4 v242, s[0:1]
	s_add_u32 m0, s14, 0x4000
	s_add_u32 s0, s16, 0x40000
	s_addc_u32 s1, s17, 0
	global_load_lds_dwordx4 v242, s[0:1]
	s_add_u32 m0, s14, 0x5000
	s_add_u32 s0, s16, 0x50000
	s_addc_u32 s1, s17, 0
	global_load_lds_dwordx4 v242, s[0:1]
	s_add_u32 m0, s14, 0x6000
	s_nop 0
	global_load_lds_dwordx4 v242, s[22:23]
	s_add_u32 m0, s14, 0x7000
	s_add_u32 s0, s22, 0x10000
	s_addc_u32 s1, s23, 0
	global_load_lds_dwordx4 v242, s[0:1]
	s_add_u32 m0, s14, 0x8000
	s_add_u32 s0, s22, 0x20000
	s_addc_u32 s1, s23, 0
	global_load_lds_dwordx4 v242, s[0:1]
	s_add_u32 m0, s14, 0x9000
	s_add_u32 s0, s22, 0x30000
	s_addc_u32 s1, s23, 0
	global_load_lds_dwordx4 v242, s[0:1]
	s_add_u32 s16, s16, 0x80
	s_addc_u32 s17, s17, 0
	s_add_u32 s22, s22, 0x80
	s_addc_u32 s23, s23, 0
	ds_read_b128 v[88:91], v240 offset:40960
	ds_read_b128 v[92:95], v240 offset:43008
	ds_read_b128 v[100:103], v240 offset:45056
	ds_read_b128 v[180:183], v240 offset:47104
	ds_read_b128 v[48:51], v238 offset:40960
	ds_read_b128 v[52:55], v238 offset:43008
	ds_read_b128 v[56:59], v238 offset:45056
	ds_read_b128 v[60:63], v238 offset:47104
	ds_read_b128 v[80:83], v238 offset:49152
	ds_read_b128 v[84:87], v238 offset:51200
	s_waitcnt lgkmcnt(5)
	v_mfma_f32_16x16x32_bf16 v[108:111], v[88:91], v[48:51], v[108:111]
	v_mfma_f32_16x16x32_bf16 v[96:99], v[92:95], v[48:51], v[96:99]
	v_mfma_f32_16x16x32_bf16 v[104:107], v[100:103], v[48:51], v[104:107]
	v_mfma_f32_16x16x32_bf16 v[116:119], v[180:183], v[48:51], v[116:119]
	s_waitcnt lgkmcnt(4)
	v_mfma_f32_16x16x32_bf16 v[76:79], v[88:91], v[52:55], v[76:79]
	v_mfma_f32_16x16x32_bf16 v[72:75], v[92:95], v[52:55], v[72:75]
	v_mfma_f32_16x16x32_bf16 v[68:71], v[100:103], v[52:55], v[68:71]
	v_mfma_f32_16x16x32_bf16 v[64:67], v[180:183], v[52:55], v[64:67]
	s_waitcnt lgkmcnt(3)
	v_mfma_f32_16x16x32_bf16 v[120:123], v[88:91], v[56:59], v[120:123]
	v_mfma_f32_16x16x32_bf16 v[124:127], v[92:95], v[56:59], v[124:127]
	v_mfma_f32_16x16x32_bf16 v[128:131], v[100:103], v[56:59], v[128:131]
	v_mfma_f32_16x16x32_bf16 v[132:135], v[180:183], v[56:59], v[132:135]
	s_waitcnt lgkmcnt(2)
	v_mfma_f32_16x16x32_bf16 v[44:47], v[88:91], v[60:63], v[44:47]
	v_mfma_f32_16x16x32_bf16 v[40:43], v[92:95], v[60:63], v[40:43]
	v_mfma_f32_16x16x32_bf16 v[36:39], v[100:103], v[60:63], v[36:39]
	v_mfma_f32_16x16x32_bf16 v[32:35], v[180:183], v[60:63], v[32:35]
	s_waitcnt lgkmcnt(1)
	v_mfma_f32_16x16x32_bf16 v[136:139], v[88:91], v[80:83], v[136:139]
	v_mfma_f32_16x16x32_bf16 v[140:143], v[92:95], v[80:83], v[140:143]
	v_mfma_f32_16x16x32_bf16 v[144:147], v[100:103], v[80:83], v[144:147]
	v_mfma_f32_16x16x32_bf16 v[148:151], v[180:183], v[80:83], v[148:151]
	s_waitcnt lgkmcnt(0)
	v_mfma_f32_16x16x32_bf16 v[28:31], v[88:91], v[84:87], v[28:31]
	v_mfma_f32_16x16x32_bf16 v[112:115], v[92:95], v[84:87], v[112:115]
	v_mfma_f32_16x16x32_bf16 v[24:27], v[100:103], v[84:87], v[24:27]
	v_mfma_f32_16x16x32_bf16 v[16:19], v[180:183], v[84:87], v[16:19]
	ds_read_b128 v[88:91], v241 offset:40960
	ds_read_b128 v[92:95], v241 offset:43008
	ds_read_b128 v[100:103], v241 offset:45056
	ds_read_b128 v[180:183], v241 offset:47104
	ds_read_b128 v[48:51], v239 offset:40960
	ds_read_b128 v[52:55], v239 offset:43008
	ds_read_b128 v[56:59], v239 offset:45056
	ds_read_b128 v[60:63], v239 offset:47104
	ds_read_b128 v[80:83], v239 offset:49152
	ds_read_b128 v[84:87], v239 offset:51200
	s_waitcnt lgkmcnt(5)
	v_mfma_f32_16x16x32_bf16 v[108:111], v[88:91], v[48:51], v[108:111]
	v_mfma_f32_16x16x32_bf16 v[96:99], v[92:95], v[48:51], v[96:99]
	v_mfma_f32_16x16x32_bf16 v[104:107], v[100:103], v[48:51], v[104:107]
	v_mfma_f32_16x16x32_bf16 v[116:119], v[180:183], v[48:51], v[116:119]
	s_waitcnt lgkmcnt(4)
	v_mfma_f32_16x16x32_bf16 v[76:79], v[88:91], v[52:55], v[76:79]
	v_mfma_f32_16x16x32_bf16 v[72:75], v[92:95], v[52:55], v[72:75]
	v_mfma_f32_16x16x32_bf16 v[68:71], v[100:103], v[52:55], v[68:71]
	v_mfma_f32_16x16x32_bf16 v[64:67], v[180:183], v[52:55], v[64:67]
	s_waitcnt lgkmcnt(3)
	v_mfma_f32_16x16x32_bf16 v[120:123], v[88:91], v[56:59], v[120:123]
	v_mfma_f32_16x16x32_bf16 v[124:127], v[92:95], v[56:59], v[124:127]
	v_mfma_f32_16x16x32_bf16 v[128:131], v[100:103], v[56:59], v[128:131]
	v_mfma_f32_16x16x32_bf16 v[132:135], v[180:183], v[56:59], v[132:135]
	s_waitcnt lgkmcnt(2)
	v_mfma_f32_16x16x32_bf16 v[44:47], v[88:91], v[60:63], v[44:47]
	v_mfma_f32_16x16x32_bf16 v[40:43], v[92:95], v[60:63], v[40:43]
	v_mfma_f32_16x16x32_bf16 v[36:39], v[100:103], v[60:63], v[36:39]
	v_mfma_f32_16x16x32_bf16 v[32:35], v[180:183], v[60:63], v[32:35]
	s_waitcnt lgkmcnt(1)
	v_mfma_f32_16x16x32_bf16 v[136:139], v[88:91], v[80:83], v[136:139]
	v_mfma_f32_16x16x32_bf16 v[140:143], v[92:95], v[80:83], v[140:143]
	v_mfma_f32_16x16x32_bf16 v[144:147], v[100:103], v[80:83], v[144:147]
	v_mfma_f32_16x16x32_bf16 v[148:151], v[180:183], v[80:83], v[148:151]
	s_waitcnt lgkmcnt(0)
	v_mfma_f32_16x16x32_bf16 v[28:31], v[88:91], v[84:87], v[28:31]
	v_mfma_f32_16x16x32_bf16 v[112:115], v[92:95], v[84:87], v[112:115]
	v_mfma_f32_16x16x32_bf16 v[24:27], v[100:103], v[84:87], v[24:27]
	v_mfma_f32_16x16x32_bf16 v[16:19], v[180:183], v[84:87], v[16:19]
	s_sub_u32 s15, s15, 1
	s_cmp_lg_u32 s15, 0
	s_cbranch_scc1 .Lk64gin_loop
	s_waitcnt vmcnt(0)
	s_barrier
	s_add_u32 m0, s14, 0xa000
	s_add_u32 s0, s24, 0x780
	s_addc_u32 s1, s25, 0
	global_load_lds_dwordx4 v243, s[0:1]
	s_add_u32 m0, s14, 0xb000
	s_add_u32 s0, s24, 0x20780
	s_addc_u32 s1, s25, 0
	global_load_lds_dwordx4 v243, s[0:1]
	s_add_u32 m0, s14, 0xc000
	s_add_u32 s0, s24, 0x40780
	s_addc_u32 s1, s25, 0
	global_load_lds_dwordx4 v243, s[0:1]
	s_add_u32 m0, s14, 0xd000
	s_add_u32 s0, s36, 0x780
	s_addc_u32 s1, s37, 0
	global_load_lds_dwordx4 v243, s[0:1]
	s_add_u32 m0, s14, 0xe000
	s_add_u32 s0, s36, 0x20780
	s_addc_u32 s1, s37, 0
	global_load_lds_dwordx4 v243, s[0:1]
	s_add_u32 m0, s14, 0xf000
	s_add_u32 s0, s24, 0x7c0
	s_addc_u32 s1, s25, 0
	global_load_lds_dwordx4 v243, s[0:1]
	s_add_u32 m0, s14, 0x10000
	s_add_u32 s0, s24, 0x207c0
	s_addc_u32 s1, s25, 0
	global_load_lds_dwordx4 v243, s[0:1]
	s_add_u32 m0, s14, 0x11000
	s_add_u32 s0, s24, 0x407c0
	s_addc_u32 s1, s25, 0
	global_load_lds_dwordx4 v243, s[0:1]
	s_add_u32 m0, s14, 0x12000
	s_add_u32 s0, s36, 0x7c0
	s_addc_u32 s1, s37, 0
	global_load_lds_dwordx4 v243, s[0:1]
	s_add_u32 m0, s14, 0x13000
	s_add_u32 s0, s36, 0x207c0
	s_addc_u32 s1, s37, 0
	global_load_lds_dwordx4 v243, s[0:1]
	ds_read_b128 v[88:91], v240 offset:0
	ds_read_b128 v[92:95], v240 offset:2048
	ds_read_b128 v[100:103], v240 offset:4096
	ds_read_b128 v[180:183], v240 offset:6144
	ds_read_b128 v[48:51], v238 offset:0
	ds_read_b128 v[52:55], v238 offset:2048
	ds_read_b128 v[56:59], v238 offset:4096
	ds_read_b128 v[60:63], v238 offset:6144
	ds_read_b128 v[80:83], v238 offset:8192
	ds_read_b128 v[84:87], v238 offset:10240
	s_waitcnt lgkmcnt(5)
	v_mfma_f32_16x16x32_bf16 v[108:111], v[88:91], v[48:51], v[108:111]
	v_mfma_f32_16x16x32_bf16 v[96:99], v[92:95], v[48:51], v[96:99]
	v_mfma_f32_16x16x32_bf16 v[104:107], v[100:103], v[48:51], v[104:107]
	v_mfma_f32_16x16x32_bf16 v[116:119], v[180:183], v[48:51], v[116:119]
	s_waitcnt lgkmcnt(4)
	v_mfma_f32_16x16x32_bf16 v[76:79], v[88:91], v[52:55], v[76:79]
	v_mfma_f32_16x16x32_bf16 v[72:75], v[92:95], v[52:55], v[72:75]
	v_mfma_f32_16x16x32_bf16 v[68:71], v[100:103], v[52:55], v[68:71]
	v_mfma_f32_16x16x32_bf16 v[64:67], v[180:183], v[52:55], v[64:67]
	s_waitcnt lgkmcnt(3)
	v_mfma_f32_16x16x32_bf16 v[120:123], v[88:91], v[56:59], v[120:123]
	v_mfma_f32_16x16x32_bf16 v[124:127], v[92:95], v[56:59], v[124:127]
	v_mfma_f32_16x16x32_bf16 v[128:131], v[100:103], v[56:59], v[128:131]
	v_mfma_f32_16x16x32_bf16 v[132:135], v[180:183], v[56:59], v[132:135]
	s_waitcnt lgkmcnt(2)
	v_mfma_f32_16x16x32_bf16 v[44:47], v[88:91], v[60:63], v[44:47]
	v_mfma_f32_16x16x32_bf16 v[40:43], v[92:95], v[60:63], v[40:43]
	v_mfma_f32_16x16x32_bf16 v[36:39], v[100:103], v[60:63], v[36:39]
	v_mfma_f32_16x16x32_bf16 v[32:35], v[180:183], v[60:63], v[32:35]
	s_waitcnt lgkmcnt(1)
	v_mfma_f32_16x16x32_bf16 v[136:139], v[88:91], v[80:83], v[136:139]
	v_mfma_f32_16x16x32_bf16 v[140:143], v[92:95], v[80:83], v[140:143]
	v_mfma_f32_16x16x32_bf16 v[144:147], v[100:103], v[80:83], v[144:147]
	v_mfma_f32_16x16x32_bf16 v[148:151], v[180:183], v[80:83], v[148:151]
	s_waitcnt lgkmcnt(0)
	v_mfma_f32_16x16x32_bf16 v[28:31], v[88:91], v[84:87], v[28:31]
	v_mfma_f32_16x16x32_bf16 v[112:115], v[92:95], v[84:87], v[112:115]
	v_mfma_f32_16x16x32_bf16 v[24:27], v[100:103], v[84:87], v[24:27]
	v_mfma_f32_16x16x32_bf16 v[16:19], v[180:183], v[84:87], v[16:19]
	ds_read_b128 v[88:91], v241 offset:0
	ds_read_b128 v[92:95], v241 offset:2048
	ds_read_b128 v[100:103], v241 offset:4096
	ds_read_b128 v[180:183], v241 offset:6144
	ds_read_b128 v[48:51], v239 offset:0
	ds_read_b128 v[52:55], v239 offset:2048
	ds_read_b128 v[56:59], v239 offset:4096
	ds_read_b128 v[60:63], v239 offset:6144
	ds_read_b128 v[80:83], v239 offset:8192
	ds_read_b128 v[84:87], v239 offset:10240
	s_waitcnt lgkmcnt(5)
	v_mfma_f32_16x16x32_bf16 v[108:111], v[88:91], v[48:51], v[108:111]
	v_mfma_f32_16x16x32_bf16 v[96:99], v[92:95], v[48:51], v[96:99]
	v_mfma_f32_16x16x32_bf16 v[104:107], v[100:103], v[48:51], v[104:107]
	v_mfma_f32_16x16x32_bf16 v[116:119], v[180:183], v[48:51], v[116:119]
	s_waitcnt lgkmcnt(4)
	v_mfma_f32_16x16x32_bf16 v[76:79], v[88:91], v[52:55], v[76:79]
	v_mfma_f32_16x16x32_bf16 v[72:75], v[92:95], v[52:55], v[72:75]
	v_mfma_f32_16x16x32_bf16 v[68:71], v[100:103], v[52:55], v[68:71]
	v_mfma_f32_16x16x32_bf16 v[64:67], v[180:183], v[52:55], v[64:67]
	s_waitcnt lgkmcnt(3)
	v_mfma_f32_16x16x32_bf16 v[120:123], v[88:91], v[56:59], v[120:123]
	v_mfma_f32_16x16x32_bf16 v[124:127], v[92:95], v[56:59], v[124:127]
	v_mfma_f32_16x16x32_bf16 v[128:131], v[100:103], v[56:59], v[128:131]
	v_mfma_f32_16x16x32_bf16 v[132:135], v[180:183], v[56:59], v[132:135]
	s_waitcnt lgkmcnt(2)
	v_mfma_f32_16x16x32_bf16 v[44:47], v[88:91], v[60:63], v[44:47]
	v_mfma_f32_16x16x32_bf16 v[40:43], v[92:95], v[60:63], v[40:43]
	v_mfma_f32_16x16x32_bf16 v[36:39], v[100:103], v[60:63], v[36:39]
	v_mfma_f32_16x16x32_bf16 v[32:35], v[180:183], v[60:63], v[32:35]
	s_waitcnt lgkmcnt(1)
	v_mfma_f32_16x16x32_bf16 v[136:139], v[88:91], v[80:83], v[136:139]
	v_mfma_f32_16x16x32_bf16 v[140:143], v[92:95], v[80:83], v[140:143]
	v_mfma_f32_16x16x32_bf16 v[144:147], v[100:103], v[80:83], v[144:147]
	v_mfma_f32_16x16x32_bf16 v[148:151], v[180:183], v[80:83], v[148:151]
	s_waitcnt lgkmcnt(0)
	v_mfma_f32_16x16x32_bf16 v[28:31], v[88:91], v[84:87], v[28:31]
	v_mfma_f32_16x16x32_bf16 v[112:115], v[92:95], v[84:87], v[112:115]
	v_mfma_f32_16x16x32_bf16 v[24:27], v[100:103], v[84:87], v[24:27]
	v_mfma_f32_16x16x32_bf16 v[16:19], v[180:183], v[84:87], v[16:19]
	s_waitcnt vmcnt(0)
	s_barrier
	s_cmp_lg_u64 s[44:45], 0
	s_cbranch_scc0 .Lk64gin_nonext
	s_mul_i32 s0, s20, 0x60000
	v_readlane_b32 s16, v249, 3
	v_readlane_b32 s17, v249, 4
	s_add_u32 s16, s16, s0
	s_addc_u32 s17, s17, 0
	s_lshl_b32 s0, s19, 18
	s_add_u32 s22, s6, s0
	s_addc_u32 s23, s7, 0
	s_add_u32 m0, s14, 0x0
	s_nop 0
	global_load_lds_dwordx4 v242, s[16:17]
	s_add_u32 m0, s14, 0x1000
	s_add_u32 s0, s16, 0x10000
	s_addc_u32 s1, s17, 0
	global_load_lds_dwordx4 v242, s[0:1]
	s_add_u32 m0, s14, 0x2000
	s_add_u32 s0, s16, 0x20000
	s_addc_u32 s1, s17, 0
	global_load_lds_dwordx4 v242, s[0:1]
	s_add_u32 m0, s14, 0x3000
	s_add_u32 s0, s16, 0x30000
	s_addc_u32 s1, s17, 0
	global_load_lds_dwordx4 v242, s[0:1]
	s_add_u32 m0, s14, 0x4000
	s_add_u32 s0, s16, 0x40000
	s_addc_u32 s1, s17, 0
	global_load_lds_dwordx4 v242, s[0:1]
	s_add_u32 m0, s14, 0x5000
	s_add_u32 s0, s16, 0x50000
	s_addc_u32 s1, s17, 0
	global_load_lds_dwordx4 v242, s[0:1]
	s_add_u32 m0, s14, 0x6000
	s_nop 0
	global_load_lds_dwordx4 v242, s[22:23]
	s_add_u32 m0, s14, 0x7000
	s_add_u32 s0, s22, 0x10000
	s_addc_u32 s1, s23, 0
	global_load_lds_dwordx4 v242, s[0:1]
	s_add_u32 m0, s14, 0x8000
	s_add_u32 s0, s22, 0x20000
	s_addc_u32 s1, s23, 0
	global_load_lds_dwordx4 v242, s[0:1]
	s_add_u32 m0, s14, 0x9000
	s_add_u32 s0, s22, 0x30000
	s_addc_u32 s1, s23, 0
	global_load_lds_dwordx4 v242, s[0:1]
.Lk64gin_nonext:
	ds_read_b128 v[88:91], v245 offset:12288
	ds_read_b128 v[92:95], v245 offset:13312
	ds_read_b128 v[100:103], v245 offset:14336
	ds_read_b128 v[180:183], v245 offset:15360
	ds_read_b128 v[48:51], v244 offset:0
	ds_read_b128 v[52:55], v244 offset:1024
	ds_read_b128 v[56:59], v244 offset:2048
	ds_read_b128 v[60:63], v244 offset:3072
	ds_read_b128 v[80:83], v244 offset:4096
	ds_read_b128 v[84:87], v244 offset:5120
	s_waitcnt lgkmcnt(5)
	v_mfma_f32_16x16x32_bf16 v[108:111], v[88:91], v[48:51], v[108:111]
	v_mfma_f32_16x16x32_bf16 v[96:99], v[92:95], v[48:51], v[96:99]
	v_mfma_f32_16x16x32_bf16 v[104:107], v[100:103], v[48:51], v[104:107]
	v_mfma_f32_16x16x32_bf16 v[116:119], v[180:183], v[48:51], v[116:119]
	s_waitcnt lgkmcnt(4)
	v_mfma_f32_16x16x32_bf16 v[76:79], v[88:91], v[52:55], v[76:79]
	v_mfma_f32_16x16x32_bf16 v[72:75], v[92:95], v[52:55], v[72:75]
	v_mfma_f32_16x16x32_bf16 v[68:71], v[100:103], v[52:55], v[68:71]
	v_mfma_f32_16x16x32_bf16 v[64:67], v[180:183], v[52:55], v[64:67]
	s_waitcnt lgkmcnt(3)
	v_mfma_f32_16x16x32_bf16 v[120:123], v[88:91], v[56:59], v[120:123]
	v_mfma_f32_16x16x32_bf16 v[124:127], v[92:95], v[56:59], v[124:127]
	v_mfma_f32_16x16x32_bf16 v[128:131], v[100:103], v[56:59], v[128:131]
	v_mfma_f32_16x16x32_bf16 v[132:135], v[180:183], v[56:59], v[132:135]
	s_waitcnt lgkmcnt(2)
	v_mfma_f32_16x16x32_bf16 v[44:47], v[88:91], v[60:63], v[44:47]
	v_mfma_f32_16x16x32_bf16 v[40:43], v[92:95], v[60:63], v[40:43]
	v_mfma_f32_16x16x32_bf16 v[36:39], v[100:103], v[60:63], v[36:39]
	v_mfma_f32_16x16x32_bf16 v[32:35], v[180:183], v[60:63], v[32:35]
	s_waitcnt lgkmcnt(1)
	v_mfma_f32_16x16x32_bf16 v[136:139], v[88:91], v[80:83], v[136:139]
	v_mfma_f32_16x16x32_bf16 v[140:143], v[92:95], v[80:83], v[140:143]
	v_mfma_f32_16x16x32_bf16 v[144:147], v[100:103], v[80:83], v[144:147]
	v_mfma_f32_16x16x32_bf16 v[148:151], v[180:183], v[80:83], v[148:151]
	s_waitcnt lgkmcnt(0)
	v_mfma_f32_16x16x32_bf16 v[28:31], v[88:91], v[84:87], v[28:31]
	v_mfma_f32_16x16x32_bf16 v[112:115], v[92:95], v[84:87], v[112:115]
	v_mfma_f32_16x16x32_bf16 v[24:27], v[100:103], v[84:87], v[24:27]
	v_mfma_f32_16x16x32_bf16 v[16:19], v[180:183], v[84:87], v[16:19]
	s_mov_b32 s31, 2
	s_mov_b32 s9, 0xf000
	s_branch .LBB0_377
.LBB0_377:
	v_lshl_add_u32 v52, v212, 1, s9
	ds_read_b128 v[20:23], v52 offset:12288
	ds_read_b128 v[180:183], v52 offset:13312
	ds_read_b128 v[234:237], v52 offset:14336
	ds_read_b128 v[238:241], v52 offset:15360
	v_lshl_add_u32 v242, v159, 1, s9
	ds_read_b128 v[48:51], v242
	s_mov_b64 s[16:17], 0
	s_mov_b64 s[14:15], 0
	s_mov_b64 s[20:21], 0
	s_waitcnt lgkmcnt(0)
	v_mfma_f32_16x16x32_bf16 v[108:111], v[20:23], v[48:51], v[108:111]
	s_mov_b64 s[10:11], 0
	s_mov_b64 s[18:19], 0
	v_mfma_f32_16x16x32_bf16 v[100:103], v[180:183], v[48:51], v[96:99]
	v_mfma_f32_16x16x32_bf16 v[104:107], v[234:237], v[48:51], v[104:107]
	v_mfma_f32_16x16x32_bf16 v[96:99], v[238:241], v[48:51], v[116:119]
	ds_read_b128 v[48:51], v242 offset:1024
	s_nop 1
	ds_read_b128 v[116:119], v242 offset:5120
	s_waitcnt lgkmcnt(0)
	v_mfma_f32_16x16x32_bf16 v[92:95], v[20:23], v[48:51], v[76:79]
	v_mfma_f32_16x16x32_bf16 v[84:87], v[180:183], v[48:51], v[72:75]
	v_mfma_f32_16x16x32_bf16 v[88:91], v[234:237], v[48:51], v[68:71]
	v_mfma_f32_16x16x32_bf16 v[80:83], v[238:241], v[48:51], v[64:67]
	ds_read_b128 v[48:51], v242 offset:2048
	s_waitcnt lgkmcnt(0)
	v_mfma_f32_16x16x32_bf16 v[76:79], v[20:23], v[48:51], v[120:123]
	v_mfma_f32_16x16x32_bf16 v[68:71], v[180:183], v[48:51], v[124:127]
	v_mfma_f32_16x16x32_bf16 v[72:75], v[234:237], v[48:51], v[128:131]
	v_mfma_f32_16x16x32_bf16 v[64:67], v[238:241], v[48:51], v[132:135]
	ds_read_b128 v[48:51], v242 offset:3072
	s_nop 0
	v_or_b32_e32 v128, s8, v213
	v_ashrrev_i32_e32 v121, 6, v128
	s_waitcnt lgkmcnt(0)
	v_mfma_f32_16x16x32_bf16 v[60:63], v[20:23], v[48:51], v[44:47]
	v_cmp_lt_i32_e32 vcc, 25, v121
	s_mov_b64 s[8:9], 0
	v_mfma_f32_16x16x32_bf16 v[52:55], v[180:183], v[48:51], v[40:43]
	v_mfma_f32_16x16x32_bf16 v[56:59], v[234:237], v[48:51], v[36:39]
	v_mfma_f32_16x16x32_bf16 v[48:51], v[238:241], v[48:51], v[32:35]
	s_nop 2
	ds_read_b128 v[32:35], v242 offset:4096
	s_waitcnt lgkmcnt(0)
	v_mfma_f32_16x16x32_bf16 v[44:47], v[20:23], v[32:35], v[136:139]
	s_nop 0
	s_barrier
	v_mfma_f32_16x16x32_bf16 v[36:39], v[180:183], v[32:35], v[140:143]
	v_mfma_f32_16x16x32_bf16 v[40:43], v[234:237], v[32:35], v[144:147]
	v_mfma_f32_16x16x32_bf16 v[32:35], v[238:241], v[32:35], v[148:151]
	v_mfma_f32_16x16x32_bf16 v[28:31], v[20:23], v[116:119], v[28:31]
	v_mfma_f32_16x16x32_bf16 v[20:23], v[180:183], v[116:119], v[112:115]
	v_mfma_f32_16x16x32_bf16 v[24:27], v[234:237], v[116:119], v[24:27]
	v_mfma_f32_16x16x32_bf16 v[16:19], v[238:241], v[116:119], v[16:19]
	s_and_saveexec_b64 s[22:23], vcc
	s_cbranch_execz .LBB0_387
	v_cmp_lt_u32_e32 vcc, 33, v121
	s_mov_b64 s[18:19], -1
	s_mov_b64 s[0:1], 0
	s_and_saveexec_b64 s[8:9], vcc
	s_cbranch_execz .LBB0_386
	v_cmp_lt_u32_e32 vcc, 35, v121
	s_mov_b64 s[10:11], -1
	s_mov_b64 s[18:19], 0
	s_mov_b64 s[24:25], 0
	s_and_saveexec_b64 s[0:1], vcc
	s_cbranch_execz .LBB0_385
	v_cmp_lt_u32_e32 vcc, 37, v121
	s_mov_b64 s[16:17], -1
	s_and_saveexec_b64 s[10:11], vcc
	s_cbranch_execz .LBB0_384
	v_cmp_lt_u32_e32 vcc, 45, v121
	s_mov_b64 s[14:15], -1
	s_and_saveexec_b64 s[16:17], vcc
	v_cmp_lt_u32_e64 s[40:41], 53, v121
	v_cmp_gt_u32_e64 s[42:43], 62, v121
	v_cmp_gt_u32_e32 vcc, 54, v121
	s_and_b64 s[14:15], s[40:41], s[42:43]
	s_and_b64 s[20:21], s[14:15], exec
	s_and_b64 s[18:19], vcc, exec
	s_xor_b64 s[14:15], exec, -1
	s_or_b64 exec, exec, s[16:17]
	s_and_b64 s[20:21], s[20:21], exec
	s_xor_b64 s[16:17], exec, -1
	s_and_b64 s[18:19], s[18:19], exec
	s_and_b64 s[14:15], s[14:15], exec

.LBB0_564:
	v_readlane_b32 s18, v247, 39
	v_readlane_b32 s26, v247, 43
	s_and_b64 vcc, exec, s[44:45]
	v_readlane_b32 s19, v247, 40
	v_readlane_b32 s27, v247, 44
	s_cbranch_vccz .LBB0_576
	s_waitcnt vmcnt(0) lgkmcnt(0)
	v_lshrrev_b32_e32 v236, 6, v167
	v_lshlrev_b32_e32 v220, 4, v186
	v_lshlrev_b32_e32 v221, 3, v186
	v_readfirstlane_b32 s2, v236
	v_xor_b32_e32 v222, 32, v186
	v_lshlrev_b32_e32 v222, 2, v222
	v_xor_b32_e32 v223, 16, v186
	v_lshlrev_b32_e32 v223, 2, v223
	v_xor_b32_e32 v224, 8, v186
	v_lshlrev_b32_e32 v224, 2, v224
	v_xor_b32_e32 v225, 4, v186
	v_lshlrev_b32_e32 v225, 2, v225
	v_xor_b32_e32 v234, 2, v186
	v_lshlrev_b32_e32 v234, 2, v234
	v_xor_b32_e32 v235, 1, v186
	v_lshlrev_b32_e32 v235, 2, v235
	v_readlane_b32 s0, v249, 0
	s_lshl_b32 s0, s0, 2
	s_add_i32 s0, s0, s2
	v_readlane_b32 s4, v249, 7
	v_readlane_b32 s5, v249, 8
	s_load_dword s1, s[4:5], 0x0
	v_readlane_b32 s20, v249, 15
	v_readlane_b32 s21, v249, 16
	s_lshl_b32 s2, s38, 12
	s_add_u32 s20, s20, s2
	s_addc_u32 s21, s21, 0
	global_load_dwordx4 v[144:147], v220, s[20:21]
	global_load_dwordx4 v[148:151], v220, s[20:21] offset:1024
	global_load_dwordx4 v[212:215], v220, s[20:21] offset:2048
	global_load_dwordx4 v[216:219], v220, s[20:21] offset:3072
	v_readlane_b32 s22, v248, 37
	v_readlane_b32 s23, v248, 38
	s_mul_i32 s2, s38, 0x12000
	s_add_u32 s22, s22, s2
	s_addc_u32 s23, s23, 0
	v_readlane_b32 s24, v249, 3
	v_readlane_b32 s25, v249, 4
	s_waitcnt lgkmcnt(0)
	s_lshl_b32 s1, s1, 2
.Lnma_pass:
	s_mul_i32 s14, s1, 0
	s_add_i32 s14, s14, s0
	s_min_u32 s14, s14, 0x17ff
	s_add_i32 s15, s14, 0xfffff000
	s_lshr_b32 s15, s15, 10
	s_add_i32 s15, s15, 1
	s_cmp_lt_u32 s14, 0x1000
	s_cselect_b32 s15, 0, s15
	s_mul_i32 s15, s15, 0x6000
	s_add_u32 s6, s22, s15
	s_addc_u32 s7, s23, 0
	s_add_u32 s8, s6, 0x1000
	s_addc_u32 s9, s7, 0
	s_lshl_b32 s15, s14, 12
	v_readlane_b32 s4, v248, 33
	v_readlane_b32 s5, v248, 34
	s_cmp_lg_u32 s38, 0
	s_cbranch_scc1 .Lnma_x0
	v_readlane_b32 s4, v249, 19
	v_readlane_b32 s5, v249, 20
	s_cmp_lt_u32 s14, 0x1000
	s_cbranch_scc1 .Lnma_x0
	v_readlane_b32 s4, v249, 21
	v_readlane_b32 s5, v249, 22
	s_add_i32 s15, s15, 0xff000000
.Lnma_x0:
	s_add_u32 s4, s4, s15
	s_addc_u32 s5, s5, 0
	global_load_dwordx4 v[0:3], v220, s[4:5]
	global_load_dwordx4 v[4:7], v220, s[4:5] offset:1024
	global_load_dwordx4 v[8:11], v220, s[4:5] offset:2048
	global_load_dwordx4 v[12:15], v220, s[4:5] offset:3072
	global_load_dwordx4 v[48:51], v220, s[6:7]
	global_load_dwordx4 v[52:55], v220, s[6:7] offset:1024
	global_load_dwordx4 v[56:59], v220, s[6:7] offset:2048
	global_load_dwordx4 v[60:63], v220, s[6:7] offset:3072
	global_load_dwordx4 v[96:99], v220, s[8:9]
	global_load_dwordx4 v[100:103], v220, s[8:9] offset:1024
	global_load_dwordx4 v[104:107], v220, s[8:9] offset:2048
	global_load_dwordx4 v[108:111], v220, s[8:9] offset:3072
	s_mul_i32 s14, s1, 1
	s_add_i32 s14, s14, s0
	s_min_u32 s14, s14, 0x17ff
	s_add_i32 s15, s14, 0xfffff000
	s_lshr_b32 s15, s15, 10
	s_add_i32 s15, s15, 1
	s_cmp_lt_u32 s14, 0x1000
	s_cselect_b32 s15, 0, s15
	s_mul_i32 s15, s15, 0x6000
	s_add_u32 s6, s22, s15
	s_addc_u32 s7, s23, 0
	s_add_u32 s8, s6, 0x1000
	s_addc_u32 s9, s7, 0
	s_lshl_b32 s15, s14, 12
	v_readlane_b32 s4, v248, 33
	v_readlane_b32 s5, v248, 34
	s_cmp_lg_u32 s38, 0
	s_cbranch_scc1 .Lnma_x1
	v_readlane_b32 s4, v249, 19
	v_readlane_b32 s5, v249, 20
	s_cmp_lt_u32 s14, 0x1000
	s_cbranch_scc1 .Lnma_x1
	v_readlane_b32 s4, v249, 21
	v_readlane_b32 s5, v249, 22
	s_add_i32 s15, s15, 0xff000000
.Lnma_x1:
	s_add_u32 s4, s4, s15
	s_addc_u32 s5, s5, 0
	global_load_dwordx4 v[16:19], v220, s[4:5]
	global_load_dwordx4 v[20:23], v220, s[4:5] offset:1024
	global_load_dwordx4 v[24:27], v220, s[4:5] offset:2048
	global_load_dwordx4 v[28:31], v220, s[4:5] offset:3072
	global_load_dwordx4 v[64:67], v220, s[6:7]
	global_load_dwordx4 v[68:71], v220, s[6:7] offset:1024
	global_load_dwordx4 v[72:75], v220, s[6:7] offset:2048
	global_load_dwordx4 v[76:79], v220, s[6:7] offset:3072
	global_load_dwordx4 v[112:115], v220, s[8:9]
	global_load_dwordx4 v[116:119], v220, s[8:9] offset:1024
	global_load_dwordx4 v[120:123], v220, s[8:9] offset:2048
	global_load_dwordx4 v[124:127], v220, s[8:9] offset:3072
	s_mul_i32 s14, s1, 2
	s_add_i32 s14, s14, s0
	s_min_u32 s14, s14, 0x17ff
	s_add_i32 s15, s14, 0xfffff000
	s_lshr_b32 s15, s15, 10
	s_add_i32 s15, s15, 1
	s_cmp_lt_u32 s14, 0x1000
	s_cselect_b32 s15, 0, s15
	s_mul_i32 s15, s15, 0x6000
	s_add_u32 s6, s22, s15
	s_addc_u32 s7, s23, 0
	s_add_u32 s8, s6, 0x1000
	s_addc_u32 s9, s7, 0
	s_lshl_b32 s15, s14, 12
	v_readlane_b32 s4, v248, 33
	v_readlane_b32 s5, v248, 34
	s_cmp_lg_u32 s38, 0
	s_cbranch_scc1 .Lnma_x2
	v_readlane_b32 s4, v249, 19
	v_readlane_b32 s5, v249, 20
	s_cmp_lt_u32 s14, 0x1000
	s_cbranch_scc1 .Lnma_x2
	v_readlane_b32 s4, v249, 21
	v_readlane_b32 s5, v249, 22
	s_add_i32 s15, s15, 0xff000000
.Lnma_x2:
	s_add_u32 s4, s4, s15
	s_addc_u32 s5, s5, 0
	global_load_dwordx4 v[32:35], v220, s[4:5]
	global_load_dwordx4 v[36:39], v220, s[4:5] offset:1024
	global_load_dwordx4 v[40:43], v220, s[4:5] offset:2048
	global_load_dwordx4 v[44:47], v220, s[4:5] offset:3072
	global_load_dwordx4 v[80:83], v220, s[6:7]
	global_load_dwordx4 v[84:87], v220, s[6:7] offset:1024
	global_load_dwordx4 v[88:91], v220, s[6:7] offset:2048
	global_load_dwordx4 v[92:95], v220, s[6:7] offset:3072
	global_load_dwordx4 v[128:131], v220, s[8:9]
	global_load_dwordx4 v[132:135], v220, s[8:9] offset:1024
	global_load_dwordx4 v[136:139], v220, s[8:9] offset:2048
	global_load_dwordx4 v[140:143], v220, s[8:9] offset:3072
	s_waitcnt vmcnt(32)
	v_mul_f32_e32 v237, v1, v1
	v_fmac_f32_e32 v237, v0, v0
	v_fmac_f32_e32 v237, v2, v2
	v_fmac_f32_e32 v237, v3, v3
	v_mul_f32_e32 v238, v5, v5
	v_fmac_f32_e32 v238, v4, v4
	v_fmac_f32_e32 v238, v6, v6
	v_fmac_f32_e32 v238, v7, v7
	v_mul_f32_e32 v239, v9, v9
	v_fmac_f32_e32 v239, v8, v8
	v_fmac_f32_e32 v239, v10, v10
	v_fmac_f32_e32 v239, v11, v11
	v_mul_f32_e32 v240, v13, v13
	v_fmac_f32_e32 v240, v12, v12
	v_fmac_f32_e32 v240, v14, v14
	v_fmac_f32_e32 v240, v15, v15
	v_add_f32_e32 v237, v237, v238
	v_add_f32_e32 v237, v237, v239
	v_add_f32_e32 v237, v237, v240
	ds_bpermute_b32 v241, v222, v237
	s_waitcnt lgkmcnt(0)
	v_add_f32_e32 v237, v237, v241
	ds_bpermute_b32 v241, v223, v237
	s_waitcnt lgkmcnt(0)
	v_add_f32_e32 v237, v237, v241
	ds_bpermute_b32 v241, v224, v237
	s_waitcnt lgkmcnt(0)
	v_add_f32_e32 v237, v237, v241
	ds_bpermute_b32 v241, v225, v237
	s_waitcnt lgkmcnt(0)
	v_add_f32_e32 v237, v237, v241
	ds_bpermute_b32 v241, v234, v237
	s_waitcnt lgkmcnt(0)
	v_add_f32_e32 v237, v237, v241
	ds_bpermute_b32 v241, v235, v237
	s_waitcnt lgkmcnt(0)
	v_add_f32_e32 v237, v237, v241
	v_fmamk_f32 v237, v237, 0x3a800000, v171
	s_mov_b32 s15, 0x800000
	v_cmp_gt_f32_e32 vcc, s15, v237
	v_mul_f32_e32 v241, 0x4b800000, v237
	s_nop 0
	v_cndmask_b32_e32 v237, v237, v241, vcc
	v_rsq_f32_e32 v237, v237
	s_nop 0
	v_mul_f32_e32 v241, 0x45800000, v237
	v_cndmask_b32_e32 v242, v237, v241, vcc
	s_waitcnt vmcnt(24)
	v_pk_mul_f32 v[0:1], v[0:1], v[242:243] op_sel_hi:[1,0]
	v_pk_mul_f32 v[0:1], v[144:145], v[0:1]
	v_pk_add_f32 v[96:97], v[96:97], 1.0 op_sel_hi:[1,0]
	v_pk_fma_f32 v[0:1], v[96:97], v[0:1], v[48:49]
	v_pk_mul_f32 v[2:3], v[2:3], v[242:243] op_sel_hi:[1,0]
	v_pk_mul_f32 v[2:3], v[146:147], v[2:3]
	v_pk_add_f32 v[98:99], v[98:99], 1.0 op_sel_hi:[1,0]
	v_pk_fma_f32 v[2:3], v[98:99], v[2:3], v[50:51]
	v_cvt_pk_bf16_f32 v0, v0, v1
	v_cvt_pk_bf16_f32 v1, v2, v3
	v_pk_mul_f32 v[4:5], v[4:5], v[242:243] op_sel_hi:[1,0]
	v_pk_mul_f32 v[4:5], v[148:149], v[4:5]
	v_pk_add_f32 v[100:101], v[100:101], 1.0 op_sel_hi:[1,0]
	v_pk_fma_f32 v[4:5], v[100:101], v[4:5], v[52:53]
	v_pk_mul_f32 v[6:7], v[6:7], v[242:243] op_sel_hi:[1,0]
	v_pk_mul_f32 v[6:7], v[150:151], v[6:7]
	v_pk_add_f32 v[102:103], v[102:103], 1.0 op_sel_hi:[1,0]
	v_pk_fma_f32 v[6:7], v[102:103], v[6:7], v[54:55]
	v_cvt_pk_bf16_f32 v4, v4, v5
	v_cvt_pk_bf16_f32 v5, v6, v7
	v_pk_mul_f32 v[8:9], v[8:9], v[242:243] op_sel_hi:[1,0]
	v_pk_mul_f32 v[8:9], v[212:213], v[8:9]
	v_pk_add_f32 v[104:105], v[104:105], 1.0 op_sel_hi:[1,0]
	v_pk_fma_f32 v[8:9], v[104:105], v[8:9], v[56:57]
	v_pk_mul_f32 v[10:11], v[10:11], v[242:243] op_sel_hi:[1,0]
	v_pk_mul_f32 v[10:11], v[214:215], v[10:11]
	v_pk_add_f32 v[106:107], v[106:107], 1.0 op_sel_hi:[1,0]
	v_pk_fma_f32 v[10:11], v[106:107], v[10:11], v[58:59]
	v_cvt_pk_bf16_f32 v8, v8, v9
	v_cvt_pk_bf16_f32 v9, v10, v11
	v_pk_mul_f32 v[12:13], v[12:13], v[242:243] op_sel_hi:[1,0]
	v_pk_mul_f32 v[12:13], v[216:217], v[12:13]
	v_pk_add_f32 v[108:109], v[108:109], 1.0 op_sel_hi:[1,0]
	v_pk_fma_f32 v[12:13], v[108:109], v[12:13], v[60:61]
	v_pk_mul_f32 v[14:15], v[14:15], v[242:243] op_sel_hi:[1,0]
	v_pk_mul_f32 v[14:15], v[218:219], v[14:15]
	v_pk_add_f32 v[110:111], v[110:111], 1.0 op_sel_hi:[1,0]
	v_pk_fma_f32 v[14:15], v[110:111], v[14:15], v[62:63]
	v_cvt_pk_bf16_f32 v12, v12, v13
	v_cvt_pk_bf16_f32 v13, v14, v15
	s_mul_i32 s14, s1, 0
	s_add_i32 s14, s14, s0
	s_cmpk_lt_u32 s14, 0x1800
	s_cbranch_scc0 .Lnma_done
	s_lshl_b32 s14, s14, 11
	s_add_u32 s10, s24, s14
	s_addc_u32 s11, s25, 0
	global_store_dwordx2 v221, v[0:1], s[10:11]
	global_store_dwordx2 v221, v[4:5], s[10:11] offset:512
	global_store_dwordx2 v221, v[8:9], s[10:11] offset:1024
	global_store_dwordx2 v221, v[12:13], s[10:11] offset:1536
	s_waitcnt vmcnt(24)
	v_mul_f32_e32 v237, v17, v17
	v_fmac_f32_e32 v237, v16, v16
	v_fmac_f32_e32 v237, v18, v18
	v_fmac_f32_e32 v237, v19, v19
	v_mul_f32_e32 v238, v21, v21
	v_fmac_f32_e32 v238, v20, v20
	v_fmac_f32_e32 v238, v22, v22
	v_fmac_f32_e32 v238, v23, v23
	v_mul_f32_e32 v239, v25, v25
	v_fmac_f32_e32 v239, v24, v24
	v_fmac_f32_e32 v239, v26, v26
	v_fmac_f32_e32 v239, v27, v27
	v_mul_f32_e32 v240, v29, v29
	v_fmac_f32_e32 v240, v28, v28
	v_fmac_f32_e32 v240, v30, v30
	v_fmac_f32_e32 v240, v31, v31
	v_add_f32_e32 v237, v237, v238
	v_add_f32_e32 v237, v237, v239
	v_add_f32_e32 v237, v237, v240
	ds_bpermute_b32 v241, v222, v237
	s_waitcnt lgkmcnt(0)
	v_add_f32_e32 v237, v237, v241
	ds_bpermute_b32 v241, v223, v237
	s_waitcnt lgkmcnt(0)
	v_add_f32_e32 v237, v237, v241
	ds_bpermute_b32 v241, v224, v237
	s_waitcnt lgkmcnt(0)
	v_add_f32_e32 v237, v237, v241
	ds_bpermute_b32 v241, v225, v237
	s_waitcnt lgkmcnt(0)
	v_add_f32_e32 v237, v237, v241
	ds_bpermute_b32 v241, v234, v237
	s_waitcnt lgkmcnt(0)
	v_add_f32_e32 v237, v237, v241
	ds_bpermute_b32 v241, v235, v237
	s_waitcnt lgkmcnt(0)
	v_add_f32_e32 v237, v237, v241
	v_fmamk_f32 v237, v237, 0x3a800000, v171
	s_mov_b32 s15, 0x800000
	v_cmp_gt_f32_e32 vcc, s15, v237
	v_mul_f32_e32 v241, 0x4b800000, v237
	s_nop 0
	v_cndmask_b32_e32 v237, v237, v241, vcc
	v_rsq_f32_e32 v237, v237
	s_nop 0
	v_mul_f32_e32 v241, 0x45800000, v237
	v_cndmask_b32_e32 v242, v237, v241, vcc
	s_waitcnt vmcnt(16)
	v_pk_mul_f32 v[16:17], v[16:17], v[242:243] op_sel_hi:[1,0]
	v_pk_mul_f32 v[16:17], v[144:145], v[16:17]
	v_pk_add_f32 v[112:113], v[112:113], 1.0 op_sel_hi:[1,0]
	v_pk_fma_f32 v[16:17], v[112:113], v[16:17], v[64:65]
	v_pk_mul_f32 v[18:19], v[18:19], v[242:243] op_sel_hi:[1,0]
	v_pk_mul_f32 v[18:19], v[146:147], v[18:19]
	v_pk_add_f32 v[114:115], v[114:115], 1.0 op_sel_hi:[1,0]
	v_pk_fma_f32 v[18:19], v[114:115], v[18:19], v[66:67]
	v_cvt_pk_bf16_f32 v16, v16, v17
	v_cvt_pk_bf16_f32 v17, v18, v19
	v_pk_mul_f32 v[20:21], v[20:21], v[242:243] op_sel_hi:[1,0]
	v_pk_mul_f32 v[20:21], v[148:149], v[20:21]
	v_pk_add_f32 v[116:117], v[116:117], 1.0 op_sel_hi:[1,0]
	v_pk_fma_f32 v[20:21], v[116:117], v[20:21], v[68:69]
	v_pk_mul_f32 v[22:23], v[22:23], v[242:243] op_sel_hi:[1,0]
	v_pk_mul_f32 v[22:23], v[150:151], v[22:23]
	v_pk_add_f32 v[118:119], v[118:119], 1.0 op_sel_hi:[1,0]
	v_pk_fma_f32 v[22:23], v[118:119], v[22:23], v[70:71]
	v_cvt_pk_bf16_f32 v20, v20, v21
	v_cvt_pk_bf16_f32 v21, v22, v23
	v_pk_mul_f32 v[24:25], v[24:25], v[242:243] op_sel_hi:[1,0]
	v_pk_mul_f32 v[24:25], v[212:213], v[24:25]
	v_pk_add_f32 v[120:121], v[120:121], 1.0 op_sel_hi:[1,0]
	v_pk_fma_f32 v[24:25], v[120:121], v[24:25], v[72:73]
	v_pk_mul_f32 v[26:27], v[26:27], v[242:243] op_sel_hi:[1,0]
	v_pk_mul_f32 v[26:27], v[214:215], v[26:27]
	v_pk_add_f32 v[122:123], v[122:123], 1.0 op_sel_hi:[1,0]
	v_pk_fma_f32 v[26:27], v[122:123], v[26:27], v[74:75]
	v_cvt_pk_bf16_f32 v24, v24, v25
	v_cvt_pk_bf16_f32 v25, v26, v27
	v_pk_mul_f32 v[28:29], v[28:29], v[242:243] op_sel_hi:[1,0]
	v_pk_mul_f32 v[28:29], v[216:217], v[28:29]
	v_pk_add_f32 v[124:125], v[124:125], 1.0 op_sel_hi:[1,0]
	v_pk_fma_f32 v[28:29], v[124:125], v[28:29], v[76:77]
	v_pk_mul_f32 v[30:31], v[30:31], v[242:243] op_sel_hi:[1,0]
	v_pk_mul_f32 v[30:31], v[218:219], v[30:31]
	v_pk_add_f32 v[126:127], v[126:127], 1.0 op_sel_hi:[1,0]
	v_pk_fma_f32 v[30:31], v[126:127], v[30:31], v[78:79]
	v_cvt_pk_bf16_f32 v28, v28, v29
	v_cvt_pk_bf16_f32 v29, v30, v31
	s_mul_i32 s14, s1, 1
	s_add_i32 s14, s14, s0
	s_cmpk_lt_u32 s14, 0x1800
	s_cbranch_scc0 .Lnma_done
	s_lshl_b32 s14, s14, 11
	s_add_u32 s10, s24, s14
	s_addc_u32 s11, s25, 0
	global_store_dwordx2 v221, v[16:17], s[10:11]
	global_store_dwordx2 v221, v[20:21], s[10:11] offset:512
	global_store_dwordx2 v221, v[24:25], s[10:11] offset:1024
	global_store_dwordx2 v221, v[28:29], s[10:11] offset:1536
	s_waitcnt vmcnt(16)
	v_mul_f32_e32 v237, v33, v33
	v_fmac_f32_e32 v237, v32, v32
	v_fmac_f32_e32 v237, v34, v34
	v_fmac_f32_e32 v237, v35, v35
	v_mul_f32_e32 v238, v37, v37
	v_fmac_f32_e32 v238, v36, v36
	v_fmac_f32_e32 v238, v38, v38
	v_fmac_f32_e32 v238, v39, v39
	v_mul_f32_e32 v239, v41, v41
	v_fmac_f32_e32 v239, v40, v40
	v_fmac_f32_e32 v239, v42, v42
	v_fmac_f32_e32 v239, v43, v43
	v_mul_f32_e32 v240, v45, v45
	v_fmac_f32_e32 v240, v44, v44
	v_fmac_f32_e32 v240, v46, v46
	v_fmac_f32_e32 v240, v47, v47
	v_add_f32_e32 v237, v237, v238
	v_add_f32_e32 v237, v237, v239
	v_add_f32_e32 v237, v237, v240
	ds_bpermute_b32 v241, v222, v237
	s_waitcnt lgkmcnt(0)
	v_add_f32_e32 v237, v237, v241
	ds_bpermute_b32 v241, v223, v237
	s_waitcnt lgkmcnt(0)
	v_add_f32_e32 v237, v237, v241
	ds_bpermute_b32 v241, v224, v237
	s_waitcnt lgkmcnt(0)
	v_add_f32_e32 v237, v237, v241
	ds_bpermute_b32 v241, v225, v237
	s_waitcnt lgkmcnt(0)
	v_add_f32_e32 v237, v237, v241
	ds_bpermute_b32 v241, v234, v237
	s_waitcnt lgkmcnt(0)
	v_add_f32_e32 v237, v237, v241
	ds_bpermute_b32 v241, v235, v237
	s_waitcnt lgkmcnt(0)
	v_add_f32_e32 v237, v237, v241
	v_fmamk_f32 v237, v237, 0x3a800000, v171
	s_mov_b32 s15, 0x800000
	v_cmp_gt_f32_e32 vcc, s15, v237
	v_mul_f32_e32 v241, 0x4b800000, v237
	s_nop 0
	v_cndmask_b32_e32 v237, v237, v241, vcc
	v_rsq_f32_e32 v237, v237
	s_nop 0
	v_mul_f32_e32 v241, 0x45800000, v237
	v_cndmask_b32_e32 v242, v237, v241, vcc
	s_waitcnt vmcnt(8)
	v_pk_mul_f32 v[32:33], v[32:33], v[242:243] op_sel_hi:[1,0]
	v_pk_mul_f32 v[32:33], v[144:145], v[32:33]
	v_pk_add_f32 v[128:129], v[128:129], 1.0 op_sel_hi:[1,0]
	v_pk_fma_f32 v[32:33], v[128:129], v[32:33], v[80:81]
	v_pk_mul_f32 v[34:35], v[34:35], v[242:243] op_sel_hi:[1,0]
	v_pk_mul_f32 v[34:35], v[146:147], v[34:35]
	v_pk_add_f32 v[130:131], v[130:131], 1.0 op_sel_hi:[1,0]
	v_pk_fma_f32 v[34:35], v[130:131], v[34:35], v[82:83]
	v_cvt_pk_bf16_f32 v32, v32, v33
	v_cvt_pk_bf16_f32 v33, v34, v35
	v_pk_mul_f32 v[36:37], v[36:37], v[242:243] op_sel_hi:[1,0]
	v_pk_mul_f32 v[36:37], v[148:149], v[36:37]
	v_pk_add_f32 v[132:133], v[132:133], 1.0 op_sel_hi:[1,0]
	v_pk_fma_f32 v[36:37], v[132:133], v[36:37], v[84:85]
	v_pk_mul_f32 v[38:39], v[38:39], v[242:243] op_sel_hi:[1,0]
	v_pk_mul_f32 v[38:39], v[150:151], v[38:39]
	v_pk_add_f32 v[134:135], v[134:135], 1.0 op_sel_hi:[1,0]
	v_pk_fma_f32 v[38:39], v[134:135], v[38:39], v[86:87]
	v_cvt_pk_bf16_f32 v36, v36, v37
	v_cvt_pk_bf16_f32 v37, v38, v39
	v_pk_mul_f32 v[40:41], v[40:41], v[242:243] op_sel_hi:[1,0]
	v_pk_mul_f32 v[40:41], v[212:213], v[40:41]
	v_pk_add_f32 v[136:137], v[136:137], 1.0 op_sel_hi:[1,0]
	v_pk_fma_f32 v[40:41], v[136:137], v[40:41], v[88:89]
	v_pk_mul_f32 v[42:43], v[42:43], v[242:243] op_sel_hi:[1,0]
	v_pk_mul_f32 v[42:43], v[214:215], v[42:43]
	v_pk_add_f32 v[138:139], v[138:139], 1.0 op_sel_hi:[1,0]
	v_pk_fma_f32 v[42:43], v[138:139], v[42:43], v[90:91]
	v_cvt_pk_bf16_f32 v40, v40, v41
	v_cvt_pk_bf16_f32 v41, v42, v43
	v_pk_mul_f32 v[44:45], v[44:45], v[242:243] op_sel_hi:[1,0]
	v_pk_mul_f32 v[44:45], v[216:217], v[44:45]
	v_pk_add_f32 v[140:141], v[140:141], 1.0 op_sel_hi:[1,0]
	v_pk_fma_f32 v[44:45], v[140:141], v[44:45], v[92:93]
	v_pk_mul_f32 v[46:47], v[46:47], v[242:243] op_sel_hi:[1,0]
	v_pk_mul_f32 v[46:47], v[218:219], v[46:47]
	v_pk_add_f32 v[142:143], v[142:143], 1.0 op_sel_hi:[1,0]
	v_pk_fma_f32 v[46:47], v[142:143], v[46:47], v[94:95]
	v_cvt_pk_bf16_f32 v44, v44, v45
	v_cvt_pk_bf16_f32 v45, v46, v47
	s_mul_i32 s14, s1, 2
	s_add_i32 s14, s14, s0
	s_cmpk_lt_u32 s14, 0x1800
	s_cbranch_scc0 .Lnma_done
	s_lshl_b32 s14, s14, 11
	s_add_u32 s10, s24, s14
	s_addc_u32 s11, s25, 0
	global_store_dwordx2 v221, v[32:33], s[10:11]
	global_store_dwordx2 v221, v[36:37], s[10:11] offset:512
	global_store_dwordx2 v221, v[40:41], s[10:11] offset:1024
	global_store_dwordx2 v221, v[44:45], s[10:11] offset:1536
	s_mul_i32 s14, s1, 3
	s_add_i32 s0, s0, s14
	s_cmpk_lt_u32 s0, 0x1800
	s_cbranch_scc1 .Lnma_pass
.Lnma_done:
	s_branch .LBB0_652
.LBB0_576:
	s_mov_b64 s[0:1], 0

.LBB0_652:
	s_add_i32 s26, s26, 1
	s_cmp_ge_i32 s26, s27
	s_mov_b64 s[0:1], -1
	s_cbranch_scc1 .LBB0_12
	v_readlane_b32 s2, v248, 43
	v_readlane_b32 s3, v248, 44
	s_and_b64 vcc, exec, s[2:3]
	s_cbranch_vccz .LBB0_703
	s_waitcnt vmcnt(0)
	s_waitcnt lgkmcnt(0)
	s_barrier
	s_mov_b64 s[2:3], exec
	v_readlane_b32 s0, v248, 45
	v_readlane_b32 s1, v248, 46
	s_and_b64 s[0:1], s[2:3], s[0:1]
	s_mov_b64 exec, s[0:1]
	s_cbranch_execz .Lbar_inv
	s_mov_b64 s[0:1], src_shared_base
	v_mov_b32_e32 v157, s1
	s_waitcnt vmcnt(0) expcnt(0) lgkmcnt(0)
	v_readlane_b32 s0, v247, 57
	s_nop 1
	v_mov_b32_e32 v2, s0
	v_mov_b32_e32 v159, s1
	v_readlane_b32 s0, v247, 58
	s_nop 1
	v_mov_b32_e32 v0, s0
	s_waitcnt vmcnt(0) lgkmcnt(0)
	v_cmp_eq_u32_e32 vcc, 0, v2
	s_and_saveexec_b64 s[4:5], vcc
	s_cbranch_execz .LBB0_670
	s_mov_b32 s10, 1
	s_branch .LBB0_658

.LBB0_669:
	v_readlane_b32 s0, v247, 23
	v_readlane_b32 s1, v247, 24
	v_cmp_ne_u32_e32 vcc, 0, v11
	s_mov_b64 s[6:7], src_shared_base
	v_cndmask_b32_e64 v16, 0, v11, s[0:1]
	v_readlane_b32 s0, v247, 21
	v_readlane_b32 s1, v247, 22
	v_cndmask_b32_e64 v11, 0, 1, vcc
	v_cmp_ne_u32_e32 vcc, 0, v0
	v_cndmask_b32_e64 v16, v16, v0, s[0:1]
	v_readlane_b32 s0, v247, 19
	v_readlane_b32 s1, v247, 20
	v_addc_co_u32_e32 v0, vcc, 0, v11, vcc
	s_nop 0
	v_cndmask_b32_e64 v16, v16, v1, s[0:1]
	v_readlane_b32 s0, v247, 17
	v_readlane_b32 s1, v247, 18
	v_cmp_ne_u32_e32 vcc, 0, v1
	v_mov_b32_e32 v157, s7
	v_cndmask_b32_e64 v16, v16, v2, s[0:1]
	v_readlane_b32 s0, v247, 15
	v_readlane_b32 s1, v247, 16
	v_cndmask_b32_e64 v1, 0, 1, vcc
	v_cmp_ne_u32_e32 vcc, 0, v2
	v_cndmask_b32_e64 v16, v16, v3, s[0:1]
	v_readlane_b32 s0, v247, 13
	v_readlane_b32 s1, v247, 14
	v_addc_co_u32_e32 v0, vcc, v0, v1, vcc
	s_nop 0
	v_cndmask_b32_e64 v16, v16, v4, s[0:1]
	v_readlane_b32 s0, v247, 11
	v_readlane_b32 s1, v247, 12
	v_cmp_ne_u32_e32 vcc, 0, v3
	v_mov_b32_e32 v159, s7
	v_cndmask_b32_e64 v16, v16, v5, s[0:1]
	v_readlane_b32 s0, v247, 9
	v_readlane_b32 s1, v247, 10
	v_cndmask_b32_e64 v1, 0, 1, vcc
	v_cmp_ne_u32_e32 vcc, 0, v4
	v_cndmask_b32_e64 v16, v16, v6, s[0:1]
	v_readlane_b32 s0, v247, 7
	v_readlane_b32 s1, v247, 8
	v_addc_co_u32_e32 v0, vcc, v0, v1, vcc
	s_nop 0
	v_cndmask_b32_e64 v16, v16, v7, s[0:1]
	v_readlane_b32 s0, v247, 5
	v_cmp_ne_u32_e32 vcc, 0, v5
	v_readlane_b32 s1, v247, 6
	s_nop 0
	v_cndmask_b32_e64 v1, 0, 1, vcc
	v_cmp_ne_u32_e32 vcc, 0, v6
	v_cndmask_b32_e64 v16, v16, v8, s[0:1]
	v_readlane_b32 s0, v247, 3
	v_addc_co_u32_e32 v0, vcc, v0, v1, vcc
	v_readlane_b32 s1, v247, 4
	v_cmp_ne_u32_e32 vcc, 0, v7
	s_nop 0
	v_cndmask_b32_e64 v16, v16, v9, s[0:1]
	v_readlane_b32 s0, v247, 1
	v_cndmask_b32_e64 v1, 0, 1, vcc
	v_cmp_ne_u32_e32 vcc, 0, v8
	v_readlane_b32 s1, v247, 2
	s_nop 0
	v_addc_co_u32_e32 v0, vcc, v0, v1, vcc
	v_cndmask_b32_e64 v16, v16, v10, s[0:1]
	v_readlane_b32 s0, v248, 63
	v_cmp_ne_u32_e32 vcc, 0, v9
	v_readlane_b32 s1, v247, 0
	s_nop 0
	v_cndmask_b32_e64 v1, 0, 1, vcc
	v_cmp_ne_u32_e32 vcc, 0, v10
	v_cndmask_b32_e64 v16, v16, v12, s[0:1]
	v_readlane_b32 s0, v248, 61
	v_addc_co_u32_e32 v0, vcc, v0, v1, vcc
	v_readlane_b32 s1, v248, 62
	v_cmp_ne_u32_e32 vcc, 0, v12
	s_nop 0
	v_cndmask_b32_e64 v16, v16, v13, s[0:1]
	v_readlane_b32 s0, v248, 59
	v_cndmask_b32_e64 v1, 0, 1, vcc
	v_cmp_ne_u32_e32 vcc, 0, v13
	v_readlane_b32 s1, v248, 60
	s_nop 0
	v_addc_co_u32_e32 v0, vcc, v0, v1, vcc
	v_cndmask_b32_e64 v16, v16, v14, s[0:1]
	v_readlane_b32 s0, v248, 57
	v_cmp_ne_u32_e32 vcc, 0, v14
	v_readlane_b32 s1, v248, 58
	s_nop 0
	v_cndmask_b32_e64 v1, 0, 1, vcc
	v_cmp_ne_u32_e32 vcc, 0, v15
	v_cndmask_b32_e64 v16, v16, v15, s[0:1]
	v_max_u32_e32 v2, 1, v16
	v_addc_co_u32_e32 v0, vcc, v0, v1, vcc
	v_max_u32_e32 v0, 1, v0
	v_readfirstlane_b32 s0, v2
	s_nop 1
	v_writelane_b32 v247, s0, 57
	v_readfirstlane_b32 s0, v0
	s_nop 1
	v_writelane_b32 v247, s0, 58

	.amdhsa_kernel _Z9trunk_fwd6Params
		.amdhsa_group_segment_fixed_size 81920
		.amdhsa_private_segment_fixed_size 0
		.amdhsa_kernarg_size 536
		.amdhsa_user_sgpr_count 2
		.amdhsa_user_sgpr_dispatch_ptr 0
		.amdhsa_user_sgpr_queue_ptr 0
		.amdhsa_user_sgpr_kernarg_segment_ptr 1
		.amdhsa_user_sgpr_dispatch_id 0
		.amdhsa_user_sgpr_kernarg_preload_length 0
		.amdhsa_user_sgpr_kernarg_preload_offset 0
		.amdhsa_user_sgpr_private_segment_size 0
		.amdhsa_uses_dynamic_stack 0
		.amdhsa_enable_private_segment 0
		.amdhsa_system_sgpr_workgroup_id_x 1
		.amdhsa_system_sgpr_workgroup_id_y 0
		.amdhsa_system_sgpr_workgroup_id_z 0
		.amdhsa_system_sgpr_workgroup_info 0
		.amdhsa_system_vgpr_workitem_id 2
		.amdhsa_next_free_vgpr 250
		.amdhsa_next_free_sgpr 102
		.amdhsa_accum_offset 252
		.amdhsa_reserve_vcc 1
		.amdhsa_float_round_mode_32 0
		.amdhsa_float_round_mode_16_64 0
		.amdhsa_float_denorm_mode_32 3
		.amdhsa_float_denorm_mode_16_64 3
		.amdhsa_dx10_clamp 1
		.amdhsa_ieee_mode 1
		.amdhsa_fp16_overflow 0
		.amdhsa_tg_split 0
		.amdhsa_exception_fp_ieee_invalid_op 0
		.amdhsa_exception_fp_denorm_src 0
		.amdhsa_exception_fp_ieee_div_zero 0
		.amdhsa_exception_fp_ieee_overflow 0
		.amdhsa_exception_fp_ieee_underflow 0
		.amdhsa_exception_fp_ieee_inexact 0
		.amdhsa_exception_int_div_zero 0
	.end_amdhsa_kernel

amdhsa.kernels:
  - .agpr_count:     0
    .args:
      - .offset:         0
        .size:           280
        .value_kind:     by_value
      - .offset:         280
        .size:           4
        .value_kind:     hidden_block_count_x
      - .offset:         284
        .size:           4
        .value_kind:     hidden_block_count_y
      - .offset:         288
        .size:           4
        .value_kind:     hidden_block_count_z
      - .offset:         292
        .size:           2
        .value_kind:     hidden_group_size_x
      - .offset:         294
        .size:           2
        .value_kind:     hidden_group_size_y
      - .offset:         296
        .size:           2
        .value_kind:     hidden_group_size_z
      - .offset:         298
        .size:           2
        .value_kind:     hidden_remainder_x
      - .offset:         300
        .size:           2
        .value_kind:     hidden_remainder_y
      - .offset:         302
        .size:           2
        .value_kind:     hidden_remainder_z
      - .offset:         320
        .size:           8
        .value_kind:     hidden_global_offset_x
      - .offset:         328
        .size:           8
        .value_kind:     hidden_global_offset_y
      - .offset:         336
        .size:           8
        .value_kind:     hidden_global_offset_z
      - .offset:         344
        .size:           2
        .value_kind:     hidden_grid_dims
      - .offset:         368
        .size:           8
        .value_kind:     hidden_multigrid_sync_arg
    .group_segment_fixed_size: 81920
    .kernarg_segment_align: 8
    .kernarg_segment_size: 536
    .language:       OpenCL C
    .language_version:
      - 2
      - 0
    .max_flat_workgroup_size: 256
    .name:           _Z9trunk_fwd6Params
    .private_segment_fixed_size: 0
    .sgpr_count:     108
    .sgpr_spill_count: 195
    .symbol:         _Z9trunk_fwd6Params.kd
    .uniform_work_group_size: 1
    .uses_dynamic_stack: false
    .vgpr_count:     250
    .vgpr_spill_count: 0
    .wavefront_size: 64
